# NSA final epilogue: 6 of 16 dwordx2 row-split stores per wave paired into dwordx4 via v_permlane32_swap (wider, fewer partial-line stores)
# baseline (speedup 1.0000x reference)
; DI unsigned pk2(float a, float b) { f2_t v = {a, b}; bf2_t r = __builtin_convertvector(v, bf2_t); return __builtin_bit_cast(unsigned, r); }
; DI float bflo(unsigned u) { return (float)__builtin_bit_cast(bf2_t, u)[0]; }
; DI float bfhi(unsigned u) { return (float)__builtin_bit_cast(bf2_t, u)[1]; }
; DI float siluf_(float x) { return x / (1.f + __expf(-x)); }
; #define NSA_GATE(c_, nb_) sigmoidf_(bf2f(zb[(size_t)qpos[nb_] * ZS + GATEC + (c_) * 8 + head]))
; DI void nsa_item(const Params& p, int l_, int item, char* lds, int dry) {
;     ...
; #pragma unroll
;   for (int nb = 0; nb < 2; ++nb) {
;     const float lt = l[nb] + shx(l[nb], lane, 32);
;     const float sc = ((lt > 0.f) ? 1.f / lt : 0.f) * NSA_GATE(2, nb);
;     u16* zr = zb + (size_t)qpos[nb] * ZS + GC + head * 64;
; #pragma unroll
;     for (int db = 0; db < 2; ++db)
; #pragma unroll
;       for (int a4 = 0; a4 < 4; ++a4) {
;         uint2* gp = (uint2*)(zr + db * 32 + 8 * a4 + 4 * h);
;         const uint2 gv = *gp;
;         const uint2 pv = *((const uint2*)&scr[((nb * 2 + db) * 2 + (a4 >> 1)) * 256] + (a4 & 1));
;         const unsigned o0 = pv.x, o1 = pv.y;
;         uint2 o;
;         o.x = pk2((bflo(o0) + O[db][nb][4 * a4] * sc) * siluf_(bflo(gv.x)),
;                   (bfhi(o0) + O[db][nb][4 * a4 + 1] * sc) * siluf_(bfhi(gv.x)));
;         o.y = pk2((bflo(o1) + O[db][nb][4 * a4 + 2] * sc) * siluf_(bflo(gv.y)),
;                   (bfhi(o1) + O[db][nb][4 * a4 + 3] * sc) * siluf_(bfhi(gv.y)));
;         if (dry) gp = (uint2*)&scr[((nb * 2 + db) * 2 + (a4 >> 1)) * 256] + (a4 & 1);
;         *gp = o;
;       }
.LBB0_769:
	ds_bpermute_b32 v0, v176, v2
	s_mov_b64 s[8:9], 0x2200
	s_movk_i32 s6, 0x2000
	v_mov_b32_e32 v10, v209
	v_readlane_b32 s4, v253, 1
	s_waitcnt lgkmcnt(0)
	v_add_f32_e32 v0, v2, v0
	v_div_scale_f32 v2, s[2:3], v0, v0, 1.0
	v_rcp_f32_e32 v3, v2
	v_cmp_lt_f32_e64 s[0:1], 0, v0
	v_readlane_b32 s5, v253, 2
	s_movk_i32 s2, 0x1000
	v_fma_f32 v4, -v2, v3, 1.0
	v_fmac_f32_e32 v3, v4, v3
	v_div_scale_f32 v4, vcc, 1.0, v0, 1.0
	v_mul_f32_e32 v5, v4, v3
	v_fma_f32 v6, -v2, v5, v4
	v_fmac_f32_e32 v5, v6, v3
	v_fma_f32 v2, -v2, v5, v4
	v_div_fmas_f32 v2, v2, v3, v5
	v_div_fixup_f32 v0, v2, v0, 1.0
	global_load_ushort v2, v[174:175], off offset:560
	v_cndmask_b32_e64 v0, 0, v0, s[0:1]
	v_readlane_b32 s18, v254, 21
	v_readlane_b32 s19, v254, 22
	v_readlane_b32 s31, v254, 1
	v_readlane_b32 s55, v254, 2
	s_mov_b32 s56, 0x800000
	s_movk_i32 s57, 0x104
	s_mov_b32 s58, 0xa480
	s_mov_b32 s59, 0x10000
	s_mov_b32 s74, 0xfffffc0
	s_movk_i32 s75, 0x3300
	s_mov_b32 s77, 0x378e98ab
	s_movk_i32 s97, 0x3000
	s_movk_i32 s96, 0x2000
	s_movk_i32 s79, 0x6000
	s_waitcnt vmcnt(0)
	v_cvt_f32_f16_e32 v2, v2
	v_mul_f32_e32 v2, 0xbfb8aa3b, v2
	v_exp_f32_e32 v2, v2
	s_nop 0
	v_add_f32_e32 v2, 1.0, v2
	v_div_scale_f32 v3, s[0:1], v2, v2, 1.0
	v_rcp_f32_e32 v4, v3
	s_nop 0
	v_fma_f32 v5, -v3, v4, 1.0
	v_fmac_f32_e32 v4, v5, v4
	v_div_scale_f32 v5, vcc, 1.0, v2, 1.0
	v_mul_f32_e32 v6, v5, v4
	v_fma_f32 v7, -v3, v6, v5
	v_fmac_f32_e32 v6, v7, v4
	v_fma_f32 v3, -v3, v6, v5
	v_div_fmas_f32 v3, v3, v4, v6
	v_div_fixup_f32 v2, v3, v2, 1.0
	v_mul_f32_e32 v2, v0, v2
	v_lshlrev_b32_e32 v0, 3, v177
	v_lshl_add_u64 v[6:7], v[172:173], 0, v[0:1]
	v_lshl_add_u64 v[4:5], v[6:7], 0, s[8:9]
	v_add_co_u32_e32 v6, vcc, s6, v6
	s_nop 1
	v_addc_co_u32_e32 v7, vcc, 0, v7, vcc
	global_load_dwordx2 v[8:9], v[6:7], off offset:512
	v_mov_b32_e32 v228, v209
	v_ashrrev_i32_e32 v229, 31, v228
	v_lshl_add_u64 v[228:229], v[228:229], 4, s[4:5]
	global_load_dwordx2 v[84:85], v[228:229], off
	global_load_dwordx2 v[86:87], v[4:5], off offset:16
	global_load_dwordx2 v[88:89], v[228:229], off offset:8
	global_load_dwordx2 v[90:91], v[4:5], off offset:32
	v_add_co_u32_e32 v230, vcc, 0x1000, v228
	s_nop 1
	v_addc_co_u32_e32 v231, vcc, 0, v229, vcc
	global_load_dwordx2 v[92:93], v[230:231], off
	global_load_dwordx2 v[94:95], v[4:5], off offset:48
	global_load_dwordx2 v[96:97], v[230:231], off offset:8
	global_load_dwordx2 v[98:99], v[4:5], off offset:64
	v_add_co_u32_e32 v230, vcc, 0x2000, v228
	s_nop 1
	v_addc_co_u32_e32 v231, vcc, 0, v229, vcc
	global_load_dwordx2 v[100:101], v[230:231], off
	global_load_dwordx2 v[102:103], v[4:5], off offset:80
	global_load_dwordx2 v[104:105], v[230:231], off offset:8
	global_load_dwordx2 v[106:107], v[4:5], off offset:96
	v_add_co_u32_e32 v230, vcc, 0x3000, v228
	s_nop 1
	v_addc_co_u32_e32 v231, vcc, 0, v229, vcc
	global_load_dwordx2 v[108:109], v[230:231], off
	global_load_dwordx2 v[110:111], v[4:5], off offset:112
	global_load_dwordx2 v[112:113], v[230:231], off offset:8
	v_and_b32_e32 v234, 32, v209
	v_lshrrev_b32_e32 v234, 2, v234
	v_add_co_u32_e32 v232, vcc, v4, v234
	s_nop 1
	v_addc_co_u32_e32 v233, vcc, 0, v5, vcc
	s_waitcnt vmcnt(15)
	v_cvt_f32_f16_sdwa v3, v8 dst_sel:DWORD dst_unused:UNUSED_PAD src0_sel:WORD_1
	v_ashrrev_i32_e32 v11, 31, v10
	v_lshl_add_u64 v[10:11], v[10:11], 4, s[4:5]
	v_cvt_f32_f16_e32 v8, v8
	v_mul_f32_e32 v12, 0xbfb8aa3b, v8
	v_exp_f32_e32 v12, v12
	s_waitcnt vmcnt(14)
	v_cvt_f32_f16_e32 v14, v84
	v_cvt_f32_f16_sdwa v15, v84 dst_sel:DWORD dst_unused:UNUSED_PAD src0_sel:WORD_1
	v_mul_f32_e32 v10, 0xbfb8aa3b, v3
	v_exp_f32_e32 v13, v10
	v_pk_fma_f32 v[14:15], v[64:65], v[2:3], v[14:15] op_sel_hi:[1,0,1]
	v_pk_add_f32 v[12:13], v[12:13], 1.0 op_sel_hi:[1,0]
	s_nop 0
	v_div_scale_f32 v10, s[0:1], v13, v13, v3
	v_rcp_f32_e32 v64, v10
	s_nop 0
	v_fma_f32 v65, -v10, v64, 1.0
	v_fmac_f32_e32 v64, v65, v64
	v_div_scale_f32 v65, vcc, v3, v13, v3
	v_mul_f32_e32 v80, v65, v64
	v_fma_f32 v81, -v10, v80, v65
	v_fmac_f32_e32 v80, v81, v64
	v_fma_f32 v10, -v10, v80, v65
	v_div_fmas_f32 v10, v10, v64, v80
	v_div_fixup_f32 v13, v10, v13, v3
	v_div_scale_f32 v3, s[0:1], v12, v12, v8
	v_rcp_f32_e32 v10, v3
	s_nop 0
	v_fma_f32 v64, -v3, v10, 1.0
	v_fmac_f32_e32 v10, v64, v10
	v_div_scale_f32 v64, vcc, v8, v12, v8
	v_mul_f32_e32 v65, v64, v10
	v_fma_f32 v80, -v3, v65, v64
	v_fmac_f32_e32 v65, v80, v10
	v_fma_f32 v3, -v3, v65, v64
	v_div_fmas_f32 v3, v3, v10, v65
	v_div_fixup_f32 v12, v3, v12, v8
	v_cvt_f32_f16_sdwa v3, v9 dst_sel:DWORD dst_unused:UNUSED_PAD src0_sel:WORD_1
	v_cvt_f32_f16_e32 v9, v9
	v_pk_mul_f32 v[12:13], v[12:13], v[14:15]
	v_mul_f32_e32 v10, 0xbfb8aa3b, v9
	v_cvt_pk_f16_f32 v8, v12, v13
	v_cvt_f32_f16_e32 v12, v85
	v_cvt_f32_f16_sdwa v13, v85 dst_sel:DWORD dst_unused:UNUSED_PAD src0_sel:WORD_1
	v_mul_f32_e32 v11, 0xbfb8aa3b, v3
	v_exp_f32_e32 v10, v10
	v_exp_f32_e32 v11, v11
	v_pk_fma_f32 v[12:13], v[66:67], v[2:3], v[12:13] op_sel_hi:[1,0,1]
	v_pk_add_f32 v[10:11], v[10:11], 1.0 op_sel_hi:[1,0]
	s_nop 0
	v_div_scale_f32 v14, s[0:1], v11, v11, v3
	v_rcp_f32_e32 v15, v14
	s_nop 0
	v_fma_f32 v64, -v14, v15, 1.0
	v_fmac_f32_e32 v15, v64, v15
	v_div_scale_f32 v64, vcc, v3, v11, v3
	v_mul_f32_e32 v65, v64, v15
	v_fma_f32 v66, -v14, v65, v64
	v_fmac_f32_e32 v65, v66, v15
	v_fma_f32 v14, -v14, v65, v64
	v_div_fmas_f32 v14, v14, v15, v65
	v_div_fixup_f32 v11, v14, v11, v3
	v_div_scale_f32 v3, s[0:1], v10, v10, v9
	v_rcp_f32_e32 v14, v3
	s_nop 0
	v_fma_f32 v15, -v3, v14, 1.0
	v_fmac_f32_e32 v14, v15, v14
	v_div_scale_f32 v15, vcc, v9, v10, v9
	v_mul_f32_e32 v64, v15, v14
	v_fma_f32 v65, -v3, v64, v15
	v_fmac_f32_e32 v64, v65, v14
	v_fma_f32 v3, -v3, v64, v15
	v_div_fmas_f32 v3, v3, v14, v64
	v_div_fixup_f32 v10, v3, v10, v9
	v_pk_mul_f32 v[10:11], v[10:11], v[12:13]
	s_nop 0
	v_cvt_pk_f16_f32 v9, v10, v11
	global_store_dwordx2 v[6:7], v[8:9], off offset:512
	v_mov_b32_e32 v8, v209
	s_waitcnt vmcnt(14)
; DI unsigned pk2(float a, float b) { f2_t v = {a, b}; bf2_t r = __builtin_convertvector(v, bf2_t); return __builtin_bit_cast(unsigned, r); }
; DI float bflo(unsigned u) { return (float)__builtin_bit_cast(bf2_t, u)[0]; }
; DI float bfhi(unsigned u) { return (float)__builtin_bit_cast(bf2_t, u)[1]; }
; DI float siluf_(float x) { return x / (1.f + __expf(-x)); }
; DI void nsa_item(const Params& p, int l_, int item, char* lds, int dry) {
;     ...
; #pragma unroll
;     for (int db = 0; db < 2; ++db)
; #pragma unroll
;       for (int a4 = 0; a4 < 4; ++a4) {
;         uint2* gp = (uint2*)(zr + db * 32 + 8 * a4 + 4 * h);
;         const uint2 gv = *gp;
;         const uint2 pv = *((const uint2*)&scr[((nb * 2 + db) * 2 + (a4 >> 1)) * 256] + (a4 & 1));
;         const unsigned o0 = pv.x, o1 = pv.y;
;         uint2 o;
;         o.x = pk2((bflo(o0) + O[db][nb][4 * a4] * sc) * siluf_(bflo(gv.x)),
;                   (bfhi(o0) + O[db][nb][4 * a4 + 1] * sc) * siluf_(bfhi(gv.x)));
;         o.y = pk2((bflo(o1) + O[db][nb][4 * a4 + 2] * sc) * siluf_(bflo(gv.y)),
;                   (bfhi(o1) + O[db][nb][4 * a4 + 3] * sc) * siluf_(bfhi(gv.y)));
;         if (dry) gp = (uint2*)&scr[((nb * 2 + db) * 2 + (a4 >> 1)) * 256] + (a4 & 1);
;         *gp = o;
;       }
	v_cvt_f32_f16_sdwa v3, v86 dst_sel:DWORD dst_unused:UNUSED_PAD src0_sel:WORD_1
	v_ashrrev_i32_e32 v9, 31, v8
	v_lshl_add_u64 v[8:9], v[8:9], 4, s[4:5]
	v_cvt_f32_f16_e32 v6, v86
	v_mul_f32_e32 v10, 0xbfb8aa3b, v6
	v_exp_f32_e32 v10, v10
	s_waitcnt vmcnt(13)
	v_cvt_f32_f16_e32 v12, v88
	v_cvt_f32_f16_sdwa v13, v88 dst_sel:DWORD dst_unused:UNUSED_PAD src0_sel:WORD_1
	v_mul_f32_e32 v8, 0xbfb8aa3b, v3
	v_exp_f32_e32 v11, v8
	v_pk_fma_f32 v[12:13], v[68:69], v[2:3], v[12:13] op_sel_hi:[1,0,1]
	v_pk_add_f32 v[10:11], v[10:11], 1.0 op_sel_hi:[1,0]
	s_nop 0
	v_div_scale_f32 v8, s[0:1], v11, v11, v3
	v_rcp_f32_e32 v14, v8
	s_nop 0
	v_fma_f32 v15, -v8, v14, 1.0
	v_fmac_f32_e32 v14, v15, v14
	v_div_scale_f32 v15, vcc, v3, v11, v3
	v_mul_f32_e32 v64, v15, v14
	v_fma_f32 v65, -v8, v64, v15
	v_fmac_f32_e32 v64, v65, v14
	v_fma_f32 v8, -v8, v64, v15
	v_div_fmas_f32 v8, v8, v14, v64
	v_div_fixup_f32 v11, v8, v11, v3
	v_div_scale_f32 v3, s[0:1], v10, v10, v6
	v_rcp_f32_e32 v8, v3
	s_nop 0
	v_fma_f32 v14, -v3, v8, 1.0
	v_fmac_f32_e32 v8, v14, v8
	v_div_scale_f32 v14, vcc, v6, v10, v6
	v_mul_f32_e32 v15, v14, v8
	v_fma_f32 v64, -v3, v15, v14
	v_fmac_f32_e32 v15, v64, v8
	v_fma_f32 v3, -v3, v15, v14
	v_div_fmas_f32 v3, v3, v8, v15
	v_div_fixup_f32 v10, v3, v10, v6
	v_cvt_f32_f16_sdwa v3, v87 dst_sel:DWORD dst_unused:UNUSED_PAD src0_sel:WORD_1
	v_cvt_f32_f16_e32 v7, v87
	v_pk_mul_f32 v[10:11], v[10:11], v[12:13]
	v_mul_f32_e32 v8, 0xbfb8aa3b, v7
	v_cvt_pk_f16_f32 v6, v10, v11
	v_cvt_f32_f16_e32 v10, v89
	v_cvt_f32_f16_sdwa v11, v89 dst_sel:DWORD dst_unused:UNUSED_PAD src0_sel:WORD_1
	v_mul_f32_e32 v9, 0xbfb8aa3b, v3
	v_exp_f32_e32 v8, v8
	v_exp_f32_e32 v9, v9
	v_pk_fma_f32 v[10:11], v[70:71], v[2:3], v[10:11] op_sel_hi:[1,0,1]
	v_pk_add_f32 v[8:9], v[8:9], 1.0 op_sel_hi:[1,0]
	s_nop 0
	v_div_scale_f32 v12, s[0:1], v9, v9, v3
	v_rcp_f32_e32 v13, v12
	s_nop 0
	v_fma_f32 v14, -v12, v13, 1.0
	v_fmac_f32_e32 v13, v14, v13
	v_div_scale_f32 v14, vcc, v3, v9, v3
	v_mul_f32_e32 v15, v14, v13
	v_fma_f32 v64, -v12, v15, v14
	v_fmac_f32_e32 v15, v64, v13
	v_fma_f32 v12, -v12, v15, v14
	v_div_fmas_f32 v12, v12, v13, v15
	v_div_fixup_f32 v9, v12, v9, v3
	v_div_scale_f32 v3, s[0:1], v8, v8, v7
	v_rcp_f32_e32 v12, v3
	s_nop 0
	v_fma_f32 v13, -v3, v12, 1.0
	v_fmac_f32_e32 v12, v13, v12
	v_div_scale_f32 v13, vcc, v7, v8, v7
	v_mul_f32_e32 v14, v13, v12
	v_fma_f32 v15, -v3, v14, v13
	v_fmac_f32_e32 v14, v15, v12
	v_fma_f32 v3, -v3, v14, v13
	v_div_fmas_f32 v3, v3, v12, v14
	v_div_fixup_f32 v8, v3, v8, v7
	v_pk_mul_f32 v[8:9], v[8:9], v[10:11]
	s_nop 0
	v_cvt_pk_f16_f32 v7, v8, v9
	v_mov_b32_e32 v8, v209
	global_store_dwordx2 v[4:5], v[6:7], off offset:16
	s_waitcnt vmcnt(13)
	v_cvt_f32_f16_sdwa v3, v90 dst_sel:DWORD dst_unused:UNUSED_PAD src0_sel:WORD_1
	v_ashrrev_i32_e32 v9, 31, v8
	v_lshl_add_u64 v[8:9], v[8:9], 4, s[4:5]
	v_add_co_u32_e32 v8, vcc, s2, v8
	v_cvt_f32_f16_e32 v6, v90
	s_nop 0
	v_addc_co_u32_e32 v9, vcc, 0, v9, vcc
	v_mul_f32_e32 v10, 0xbfb8aa3b, v6
	v_exp_f32_e32 v10, v10
	s_waitcnt vmcnt(12)
	v_cvt_f32_f16_e32 v12, v92
	v_cvt_f32_f16_sdwa v13, v92 dst_sel:DWORD dst_unused:UNUSED_PAD src0_sel:WORD_1
	v_mul_f32_e32 v8, 0xbfb8aa3b, v3
	v_exp_f32_e32 v11, v8
	v_pk_fma_f32 v[12:13], v[72:73], v[2:3], v[12:13] op_sel_hi:[1,0,1]
	v_pk_add_f32 v[10:11], v[10:11], 1.0 op_sel_hi:[1,0]
	s_nop 0
	v_div_scale_f32 v8, s[0:1], v11, v11, v3
	v_rcp_f32_e32 v14, v8
	s_nop 0
	v_fma_f32 v15, -v8, v14, 1.0
	v_fmac_f32_e32 v14, v15, v14
	v_div_scale_f32 v15, vcc, v3, v11, v3
	v_mul_f32_e32 v64, v15, v14
	v_fma_f32 v65, -v8, v64, v15
	v_fmac_f32_e32 v64, v65, v14
	v_fma_f32 v8, -v8, v64, v15
	v_div_fmas_f32 v8, v8, v14, v64
	v_div_fixup_f32 v11, v8, v11, v3
	v_div_scale_f32 v3, s[0:1], v10, v10, v6
	v_rcp_f32_e32 v8, v3
	s_nop 0
	v_fma_f32 v14, -v3, v8, 1.0
	v_fmac_f32_e32 v8, v14, v8
	v_div_scale_f32 v14, vcc, v6, v10, v6
	v_mul_f32_e32 v15, v14, v8
	v_fma_f32 v64, -v3, v15, v14
	v_fmac_f32_e32 v15, v64, v8
	v_fma_f32 v3, -v3, v15, v14
	v_div_fmas_f32 v3, v3, v8, v15
	v_div_fixup_f32 v10, v3, v10, v6
	v_cvt_f32_f16_sdwa v3, v91 dst_sel:DWORD dst_unused:UNUSED_PAD src0_sel:WORD_1
	v_cvt_f32_f16_e32 v7, v91
	v_pk_mul_f32 v[10:11], v[10:11], v[12:13]
	v_mul_f32_e32 v8, 0xbfb8aa3b, v7
	v_cvt_pk_f16_f32 v6, v10, v11
	v_cvt_f32_f16_e32 v10, v93
	v_cvt_f32_f16_sdwa v11, v93 dst_sel:DWORD dst_unused:UNUSED_PAD src0_sel:WORD_1
	v_mul_f32_e32 v9, 0xbfb8aa3b, v3
	v_exp_f32_e32 v8, v8
	v_exp_f32_e32 v9, v9
	v_pk_fma_f32 v[10:11], v[74:75], v[2:3], v[10:11] op_sel_hi:[1,0,1]
	v_pk_add_f32 v[8:9], v[8:9], 1.0 op_sel_hi:[1,0]
	s_nop 0
	v_div_scale_f32 v12, s[0:1], v9, v9, v3
	v_rcp_f32_e32 v13, v12
	s_nop 0
	v_fma_f32 v14, -v12, v13, 1.0
	v_fmac_f32_e32 v13, v14, v13
	v_div_scale_f32 v14, vcc, v3, v9, v3
	v_mul_f32_e32 v15, v14, v13
	v_fma_f32 v64, -v12, v15, v14
	v_fmac_f32_e32 v15, v64, v13
	v_fma_f32 v12, -v12, v15, v14
	v_div_fmas_f32 v12, v12, v13, v15
	v_div_fixup_f32 v9, v12, v9, v3
	v_div_scale_f32 v3, s[0:1], v8, v8, v7
	v_rcp_f32_e32 v12, v3
	s_nop 0
	v_fma_f32 v13, -v3, v12, 1.0
	v_fmac_f32_e32 v12, v13, v12
	v_div_scale_f32 v13, vcc, v7, v8, v7
	v_mul_f32_e32 v14, v13, v12
	v_fma_f32 v15, -v3, v14, v13
	v_fmac_f32_e32 v14, v15, v12
	v_fma_f32 v3, -v3, v14, v13
	v_div_fmas_f32 v3, v3, v12, v14
	v_div_fixup_f32 v8, v3, v8, v7
	v_pk_mul_f32 v[8:9], v[8:9], v[10:11]
	s_nop 0
	v_cvt_pk_f16_f32 v7, v8, v9
	v_mov_b32_e32 v8, v209
	v_mov_b32_e32 v246, v6
	v_mov_b32_e32 v247, v7
	s_waitcnt vmcnt(11)
	v_cvt_f32_f16_sdwa v3, v94 dst_sel:DWORD dst_unused:UNUSED_PAD src0_sel:WORD_1
	v_ashrrev_i32_e32 v9, 31, v8
	v_lshl_add_u64 v[8:9], v[8:9], 4, s[4:5]
	v_add_co_u32_e32 v8, vcc, s2, v8
	v_cvt_f32_f16_e32 v6, v94
	s_nop 0
	v_addc_co_u32_e32 v9, vcc, 0, v9, vcc
	v_mul_f32_e32 v10, 0xbfb8aa3b, v6
	v_exp_f32_e32 v10, v10
	s_movk_i32 s2, 0x3000
	s_waitcnt vmcnt(10)
; DI unsigned pk2(float a, float b) { f2_t v = {a, b}; bf2_t r = __builtin_convertvector(v, bf2_t); return __builtin_bit_cast(unsigned, r); }
; DI float bflo(unsigned u) { return (float)__builtin_bit_cast(bf2_t, u)[0]; }
; DI float bfhi(unsigned u) { return (float)__builtin_bit_cast(bf2_t, u)[1]; }
; DI float siluf_(float x) { return x / (1.f + __expf(-x)); }
; DI void nsa_item(const Params& p, int l_, int item, char* lds, int dry) {
;     ...
; #pragma unroll
;     for (int db = 0; db < 2; ++db)
; #pragma unroll
;       for (int a4 = 0; a4 < 4; ++a4) {
;         uint2* gp = (uint2*)(zr + db * 32 + 8 * a4 + 4 * h);
;         const uint2 gv = *gp;
;         const uint2 pv = *((const uint2*)&scr[((nb * 2 + db) * 2 + (a4 >> 1)) * 256] + (a4 & 1));
;         const unsigned o0 = pv.x, o1 = pv.y;
;         uint2 o;
;         o.x = pk2((bflo(o0) + O[db][nb][4 * a4] * sc) * siluf_(bflo(gv.x)),
;                   (bfhi(o0) + O[db][nb][4 * a4 + 1] * sc) * siluf_(bfhi(gv.x)));
;         o.y = pk2((bflo(o1) + O[db][nb][4 * a4 + 2] * sc) * siluf_(bflo(gv.y)),
;                   (bfhi(o1) + O[db][nb][4 * a4 + 3] * sc) * siluf_(bfhi(gv.y)));
;         if (dry) gp = (uint2*)&scr[((nb * 2 + db) * 2 + (a4 >> 1)) * 256] + (a4 & 1);
;         *gp = o;
;       }
	v_cvt_f32_f16_e32 v12, v96
	v_cvt_f32_f16_sdwa v13, v96 dst_sel:DWORD dst_unused:UNUSED_PAD src0_sel:WORD_1
	v_mul_f32_e32 v8, 0xbfb8aa3b, v3
	v_exp_f32_e32 v11, v8
	v_pk_fma_f32 v[12:13], v[76:77], v[2:3], v[12:13] op_sel_hi:[1,0,1]
	v_pk_add_f32 v[10:11], v[10:11], 1.0 op_sel_hi:[1,0]
	s_nop 0
	v_div_scale_f32 v8, s[0:1], v11, v11, v3
	v_rcp_f32_e32 v14, v8
	s_nop 0
	v_fma_f32 v15, -v8, v14, 1.0
	v_fmac_f32_e32 v14, v15, v14
	v_div_scale_f32 v15, vcc, v3, v11, v3
	v_mul_f32_e32 v64, v15, v14
	v_fma_f32 v65, -v8, v64, v15
	v_fmac_f32_e32 v64, v65, v14
	v_fma_f32 v8, -v8, v64, v15
	v_div_fmas_f32 v8, v8, v14, v64
	v_div_fixup_f32 v11, v8, v11, v3
	v_div_scale_f32 v3, s[0:1], v10, v10, v6
	v_rcp_f32_e32 v8, v3
	s_nop 0
	v_fma_f32 v14, -v3, v8, 1.0
	v_fmac_f32_e32 v8, v14, v8
	v_div_scale_f32 v14, vcc, v6, v10, v6
	v_mul_f32_e32 v15, v14, v8
	v_fma_f32 v64, -v3, v15, v14
	v_fmac_f32_e32 v15, v64, v8
	v_fma_f32 v3, -v3, v15, v14
	v_div_fmas_f32 v3, v3, v8, v15
	v_div_fixup_f32 v10, v3, v10, v6
	v_cvt_f32_f16_sdwa v3, v95 dst_sel:DWORD dst_unused:UNUSED_PAD src0_sel:WORD_1
	v_cvt_f32_f16_e32 v7, v95
	v_pk_mul_f32 v[10:11], v[10:11], v[12:13]
	v_mul_f32_e32 v8, 0xbfb8aa3b, v7
	v_cvt_pk_f16_f32 v6, v10, v11
	v_cvt_f32_f16_e32 v10, v97
	v_cvt_f32_f16_sdwa v11, v97 dst_sel:DWORD dst_unused:UNUSED_PAD src0_sel:WORD_1
	v_mul_f32_e32 v9, 0xbfb8aa3b, v3
	v_exp_f32_e32 v8, v8
	v_exp_f32_e32 v9, v9
	v_pk_fma_f32 v[10:11], v[78:79], v[2:3], v[10:11] op_sel_hi:[1,0,1]
	v_pk_add_f32 v[8:9], v[8:9], 1.0 op_sel_hi:[1,0]
	s_nop 0
	v_div_scale_f32 v12, s[0:1], v9, v9, v3
	v_rcp_f32_e32 v13, v12
	s_nop 0
	v_fma_f32 v14, -v12, v13, 1.0
	v_fmac_f32_e32 v13, v14, v13
	v_div_scale_f32 v14, vcc, v3, v9, v3
	v_mul_f32_e32 v15, v14, v13
	v_fma_f32 v64, -v12, v15, v14
	v_fmac_f32_e32 v15, v64, v13
	v_fma_f32 v12, -v12, v15, v14
	v_div_fmas_f32 v12, v12, v13, v15
	v_div_fixup_f32 v9, v12, v9, v3
	v_div_scale_f32 v3, s[0:1], v8, v8, v7
	v_rcp_f32_e32 v12, v3
	s_nop 0
	v_fma_f32 v13, -v3, v12, 1.0
	v_fmac_f32_e32 v12, v13, v12
	v_div_scale_f32 v13, vcc, v7, v8, v7
	v_mul_f32_e32 v14, v13, v12
	v_fma_f32 v15, -v3, v14, v13
	v_fmac_f32_e32 v14, v15, v12
	v_fma_f32 v3, -v3, v14, v13
	v_div_fmas_f32 v3, v3, v12, v14
	v_div_fixup_f32 v8, v3, v8, v7
	v_pk_mul_f32 v[8:9], v[8:9], v[10:11]
	s_nop 0
	v_cvt_pk_f16_f32 v7, v8, v9
	v_mov_b32_e32 v8, v209
	v_mov_b32_e32 v248, v6
	v_mov_b32_e32 v249, v7
	s_nop 1
	v_permlane32_swap_b32 v246, v248
	v_permlane32_swap_b32 v247, v249
	global_store_dwordx4 v[232:233], v[246:249], off offset:32
	s_waitcnt vmcnt(10)
	v_cvt_f32_f16_sdwa v3, v98 dst_sel:DWORD dst_unused:UNUSED_PAD src0_sel:WORD_1
	v_ashrrev_i32_e32 v9, 31, v8
	v_lshl_add_u64 v[8:9], v[8:9], 4, s[4:5]
	v_add_co_u32_e32 v8, vcc, s6, v8
	v_cvt_f32_f16_e32 v6, v98
	s_nop 0
	v_addc_co_u32_e32 v9, vcc, 0, v9, vcc
	v_mul_f32_e32 v10, 0xbfb8aa3b, v6
	v_exp_f32_e32 v10, v10
	s_waitcnt vmcnt(9)
	v_cvt_f32_f16_e32 v12, v100
	v_cvt_f32_f16_sdwa v13, v100 dst_sel:DWORD dst_unused:UNUSED_PAD src0_sel:WORD_1
	v_mul_f32_e32 v8, 0xbfb8aa3b, v3
	v_exp_f32_e32 v11, v8
	v_pk_fma_f32 v[12:13], v[48:49], v[2:3], v[12:13] op_sel_hi:[1,0,1]
	v_pk_add_f32 v[10:11], v[10:11], 1.0 op_sel_hi:[1,0]
	s_nop 0
	v_div_scale_f32 v8, s[0:1], v11, v11, v3
	v_rcp_f32_e32 v14, v8
	s_nop 0
	v_fma_f32 v15, -v8, v14, 1.0
	v_fmac_f32_e32 v14, v15, v14
	v_div_scale_f32 v15, vcc, v3, v11, v3
	v_mul_f32_e32 v48, v15, v14
	v_fma_f32 v49, -v8, v48, v15
	v_fmac_f32_e32 v48, v49, v14
	v_fma_f32 v8, -v8, v48, v15
	v_div_fmas_f32 v8, v8, v14, v48
	v_div_fixup_f32 v11, v8, v11, v3
	v_div_scale_f32 v3, s[0:1], v10, v10, v6
	v_rcp_f32_e32 v8, v3
	s_nop 0
	v_fma_f32 v14, -v3, v8, 1.0
	v_fmac_f32_e32 v8, v14, v8
	v_div_scale_f32 v14, vcc, v6, v10, v6
	v_mul_f32_e32 v15, v14, v8
	v_fma_f32 v48, -v3, v15, v14
	v_fmac_f32_e32 v15, v48, v8
	v_fma_f32 v3, -v3, v15, v14
	v_div_fmas_f32 v3, v3, v8, v15
	v_div_fixup_f32 v10, v3, v10, v6
	v_cvt_f32_f16_sdwa v3, v99 dst_sel:DWORD dst_unused:UNUSED_PAD src0_sel:WORD_1
	v_cvt_f32_f16_e32 v7, v99
	v_pk_mul_f32 v[10:11], v[10:11], v[12:13]
	v_mul_f32_e32 v8, 0xbfb8aa3b, v7
	v_cvt_pk_f16_f32 v6, v10, v11
	v_cvt_f32_f16_e32 v10, v101
	v_cvt_f32_f16_sdwa v11, v101 dst_sel:DWORD dst_unused:UNUSED_PAD src0_sel:WORD_1
	v_mul_f32_e32 v9, 0xbfb8aa3b, v3
	v_exp_f32_e32 v8, v8
	v_exp_f32_e32 v9, v9
	v_pk_fma_f32 v[10:11], v[50:51], v[2:3], v[10:11] op_sel_hi:[1,0,1]
	v_pk_add_f32 v[8:9], v[8:9], 1.0 op_sel_hi:[1,0]
	s_nop 0
	v_div_scale_f32 v12, s[0:1], v9, v9, v3
	v_rcp_f32_e32 v13, v12
	s_nop 0
	v_fma_f32 v14, -v12, v13, 1.0
	v_fmac_f32_e32 v13, v14, v13
	v_div_scale_f32 v14, vcc, v3, v9, v3
	v_mul_f32_e32 v15, v14, v13
	v_fma_f32 v48, -v12, v15, v14
	v_fmac_f32_e32 v15, v48, v13
	v_fma_f32 v12, -v12, v15, v14
	v_div_fmas_f32 v12, v12, v13, v15
	v_div_fixup_f32 v9, v12, v9, v3
	v_div_scale_f32 v3, s[0:1], v8, v8, v7
	v_rcp_f32_e32 v12, v3
	s_nop 0
	v_fma_f32 v13, -v3, v12, 1.0
	v_fmac_f32_e32 v12, v13, v12
	v_div_scale_f32 v13, vcc, v7, v8, v7
	v_mul_f32_e32 v14, v13, v12
	v_fma_f32 v15, -v3, v14, v13
	v_fmac_f32_e32 v14, v15, v12
	v_fma_f32 v3, -v3, v14, v13
	v_div_fmas_f32 v3, v3, v12, v14
	v_div_fixup_f32 v8, v3, v8, v7
	v_pk_mul_f32 v[8:9], v[8:9], v[10:11]
	s_nop 0
	v_cvt_pk_f16_f32 v7, v8, v9
	v_mov_b32_e32 v8, v209
	v_mov_b32_e32 v246, v6
	v_mov_b32_e32 v247, v7
	s_waitcnt vmcnt(8)
	v_cvt_f32_f16_sdwa v3, v102 dst_sel:DWORD dst_unused:UNUSED_PAD src0_sel:WORD_1
	v_ashrrev_i32_e32 v9, 31, v8
	v_lshl_add_u64 v[8:9], v[8:9], 4, s[4:5]
	v_add_co_u32_e32 v8, vcc, s6, v8
	v_cvt_f32_f16_e32 v6, v102
	s_nop 0
	v_addc_co_u32_e32 v9, vcc, 0, v9, vcc
	v_mul_f32_e32 v10, 0xbfb8aa3b, v6
	v_exp_f32_e32 v10, v10
	s_waitcnt vmcnt(7)
; DI unsigned pk2(float a, float b) { f2_t v = {a, b}; bf2_t r = __builtin_convertvector(v, bf2_t); return __builtin_bit_cast(unsigned, r); }
; DI float bflo(unsigned u) { return (float)__builtin_bit_cast(bf2_t, u)[0]; }
; DI float bfhi(unsigned u) { return (float)__builtin_bit_cast(bf2_t, u)[1]; }
; DI float siluf_(float x) { return x / (1.f + __expf(-x)); }
; DI void nsa_item(const Params& p, int l_, int item, char* lds, int dry) {
;     ...
; #pragma unroll
;     for (int db = 0; db < 2; ++db)
; #pragma unroll
;       for (int a4 = 0; a4 < 4; ++a4) {
;         uint2* gp = (uint2*)(zr + db * 32 + 8 * a4 + 4 * h);
;         const uint2 gv = *gp;
;         const uint2 pv = *((const uint2*)&scr[((nb * 2 + db) * 2 + (a4 >> 1)) * 256] + (a4 & 1));
;         const unsigned o0 = pv.x, o1 = pv.y;
;         uint2 o;
;         o.x = pk2((bflo(o0) + O[db][nb][4 * a4] * sc) * siluf_(bflo(gv.x)),
;                   (bfhi(o0) + O[db][nb][4 * a4 + 1] * sc) * siluf_(bfhi(gv.x)));
;         o.y = pk2((bflo(o1) + O[db][nb][4 * a4 + 2] * sc) * siluf_(bflo(gv.y)),
;                   (bfhi(o1) + O[db][nb][4 * a4 + 3] * sc) * siluf_(bfhi(gv.y)));
;         if (dry) gp = (uint2*)&scr[((nb * 2 + db) * 2 + (a4 >> 1)) * 256] + (a4 & 1);
;         *gp = o;
;       }
	v_cvt_f32_f16_e32 v12, v104
	v_cvt_f32_f16_sdwa v13, v104 dst_sel:DWORD dst_unused:UNUSED_PAD src0_sel:WORD_1
	v_mul_f32_e32 v8, 0xbfb8aa3b, v3
	v_exp_f32_e32 v11, v8
	v_pk_fma_f32 v[12:13], v[52:53], v[2:3], v[12:13] op_sel_hi:[1,0,1]
	v_pk_add_f32 v[10:11], v[10:11], 1.0 op_sel_hi:[1,0]
	s_nop 0
	v_div_scale_f32 v8, s[0:1], v11, v11, v3
	v_rcp_f32_e32 v14, v8
	s_nop 0
	v_fma_f32 v15, -v8, v14, 1.0
	v_fmac_f32_e32 v14, v15, v14
	v_div_scale_f32 v15, vcc, v3, v11, v3
	v_mul_f32_e32 v48, v15, v14
	v_fma_f32 v49, -v8, v48, v15
	v_fmac_f32_e32 v48, v49, v14
	v_fma_f32 v8, -v8, v48, v15
	v_div_fmas_f32 v8, v8, v14, v48
	v_div_fixup_f32 v11, v8, v11, v3
	v_div_scale_f32 v3, s[0:1], v10, v10, v6
	v_rcp_f32_e32 v8, v3
	s_nop 0
	v_fma_f32 v14, -v3, v8, 1.0
	v_fmac_f32_e32 v8, v14, v8
	v_div_scale_f32 v14, vcc, v6, v10, v6
	v_mul_f32_e32 v15, v14, v8
	v_fma_f32 v48, -v3, v15, v14
	v_fmac_f32_e32 v15, v48, v8
	v_fma_f32 v3, -v3, v15, v14
	v_div_fmas_f32 v3, v3, v8, v15
	v_div_fixup_f32 v10, v3, v10, v6
	v_cvt_f32_f16_sdwa v3, v103 dst_sel:DWORD dst_unused:UNUSED_PAD src0_sel:WORD_1
	v_cvt_f32_f16_e32 v7, v103
	v_pk_mul_f32 v[10:11], v[10:11], v[12:13]
	v_mul_f32_e32 v8, 0xbfb8aa3b, v7
	v_cvt_pk_f16_f32 v6, v10, v11
	v_cvt_f32_f16_e32 v10, v105
	v_cvt_f32_f16_sdwa v11, v105 dst_sel:DWORD dst_unused:UNUSED_PAD src0_sel:WORD_1
	v_mul_f32_e32 v9, 0xbfb8aa3b, v3
	v_exp_f32_e32 v8, v8
	v_exp_f32_e32 v9, v9
	v_pk_fma_f32 v[10:11], v[54:55], v[2:3], v[10:11] op_sel_hi:[1,0,1]
	v_pk_add_f32 v[8:9], v[8:9], 1.0 op_sel_hi:[1,0]
	s_nop 0
	v_div_scale_f32 v12, s[0:1], v9, v9, v3
	v_rcp_f32_e32 v13, v12
	s_nop 0
	v_fma_f32 v14, -v12, v13, 1.0
	v_fmac_f32_e32 v13, v14, v13
	v_div_scale_f32 v14, vcc, v3, v9, v3
	v_mul_f32_e32 v15, v14, v13
	v_fma_f32 v48, -v12, v15, v14
	v_fmac_f32_e32 v15, v48, v13
	v_fma_f32 v12, -v12, v15, v14
	v_div_fmas_f32 v12, v12, v13, v15
	v_div_fixup_f32 v9, v12, v9, v3
	v_div_scale_f32 v3, s[0:1], v8, v8, v7
	v_rcp_f32_e32 v12, v3
	s_nop 0
	v_fma_f32 v13, -v3, v12, 1.0
	v_fmac_f32_e32 v12, v13, v12
	v_div_scale_f32 v13, vcc, v7, v8, v7
	v_mul_f32_e32 v14, v13, v12
	v_fma_f32 v15, -v3, v14, v13
	v_fmac_f32_e32 v14, v15, v12
	v_fma_f32 v3, -v3, v14, v13
	v_div_fmas_f32 v3, v3, v12, v14
	v_div_fixup_f32 v8, v3, v8, v7
	v_pk_mul_f32 v[8:9], v[8:9], v[10:11]
	s_nop 0
	v_cvt_pk_f16_f32 v7, v8, v9
	v_mov_b32_e32 v8, v209
	v_mov_b32_e32 v248, v6
	v_mov_b32_e32 v249, v7
	s_nop 1
	v_permlane32_swap_b32 v246, v248
	v_permlane32_swap_b32 v247, v249
	global_store_dwordx4 v[232:233], v[246:249], off offset:64
	s_waitcnt vmcnt(7)
	v_cvt_f32_f16_sdwa v3, v106 dst_sel:DWORD dst_unused:UNUSED_PAD src0_sel:WORD_1
	v_ashrrev_i32_e32 v9, 31, v8
	v_lshl_add_u64 v[8:9], v[8:9], 4, s[4:5]
	v_add_co_u32_e32 v8, vcc, s2, v8
	v_cvt_f32_f16_e32 v6, v106
	s_nop 0
	v_addc_co_u32_e32 v9, vcc, 0, v9, vcc
	v_mul_f32_e32 v10, 0xbfb8aa3b, v6
	v_exp_f32_e32 v10, v10
	s_waitcnt vmcnt(6)
	v_cvt_f32_f16_e32 v12, v108
	v_cvt_f32_f16_sdwa v13, v108 dst_sel:DWORD dst_unused:UNUSED_PAD src0_sel:WORD_1
	v_mul_f32_e32 v8, 0xbfb8aa3b, v3
	v_exp_f32_e32 v11, v8
	v_pk_fma_f32 v[12:13], v[56:57], v[2:3], v[12:13] op_sel_hi:[1,0,1]
	v_pk_add_f32 v[10:11], v[10:11], 1.0 op_sel_hi:[1,0]
	s_nop 0
	v_div_scale_f32 v8, s[0:1], v11, v11, v3
	v_rcp_f32_e32 v14, v8
	s_nop 0
	v_fma_f32 v15, -v8, v14, 1.0
	v_fmac_f32_e32 v14, v15, v14
	v_div_scale_f32 v15, vcc, v3, v11, v3
	v_mul_f32_e32 v48, v15, v14
	v_fma_f32 v49, -v8, v48, v15
	v_fmac_f32_e32 v48, v49, v14
	v_fma_f32 v8, -v8, v48, v15
	v_div_fmas_f32 v8, v8, v14, v48
	v_div_fixup_f32 v11, v8, v11, v3
	v_div_scale_f32 v3, s[0:1], v10, v10, v6
	v_rcp_f32_e32 v8, v3
	s_nop 0
	v_fma_f32 v14, -v3, v8, 1.0
	v_fmac_f32_e32 v8, v14, v8
	v_div_scale_f32 v14, vcc, v6, v10, v6
	v_mul_f32_e32 v15, v14, v8
	v_fma_f32 v48, -v3, v15, v14
	v_fmac_f32_e32 v15, v48, v8
	v_fma_f32 v3, -v3, v15, v14
	v_div_fmas_f32 v3, v3, v8, v15
	v_div_fixup_f32 v10, v3, v10, v6
	v_cvt_f32_f16_sdwa v3, v107 dst_sel:DWORD dst_unused:UNUSED_PAD src0_sel:WORD_1
	v_cvt_f32_f16_e32 v7, v107
	v_pk_mul_f32 v[10:11], v[10:11], v[12:13]
	v_mul_f32_e32 v8, 0xbfb8aa3b, v7
	v_cvt_pk_f16_f32 v6, v10, v11
	v_cvt_f32_f16_e32 v10, v109
	v_cvt_f32_f16_sdwa v11, v109 dst_sel:DWORD dst_unused:UNUSED_PAD src0_sel:WORD_1
	v_mul_f32_e32 v9, 0xbfb8aa3b, v3
	v_exp_f32_e32 v8, v8
	v_exp_f32_e32 v9, v9
	v_pk_fma_f32 v[10:11], v[58:59], v[2:3], v[10:11] op_sel_hi:[1,0,1]
	v_pk_add_f32 v[8:9], v[8:9], 1.0 op_sel_hi:[1,0]
	s_nop 0
	v_div_scale_f32 v12, s[0:1], v9, v9, v3
	v_rcp_f32_e32 v13, v12
	s_nop 0
	v_fma_f32 v14, -v12, v13, 1.0
	v_fmac_f32_e32 v13, v14, v13
	v_div_scale_f32 v14, vcc, v3, v9, v3
	v_mul_f32_e32 v15, v14, v13
	v_fma_f32 v48, -v12, v15, v14
	v_fmac_f32_e32 v15, v48, v13
	v_fma_f32 v12, -v12, v15, v14
	v_div_fmas_f32 v12, v12, v13, v15
	v_div_fixup_f32 v9, v12, v9, v3
	v_div_scale_f32 v3, s[0:1], v8, v8, v7
	v_rcp_f32_e32 v12, v3
	s_nop 0
	v_fma_f32 v13, -v3, v12, 1.0
	v_fmac_f32_e32 v12, v13, v12
	v_div_scale_f32 v13, vcc, v7, v8, v7
	v_mul_f32_e32 v14, v13, v12
	v_fma_f32 v15, -v3, v14, v13
	v_fmac_f32_e32 v14, v15, v12
	v_fma_f32 v3, -v3, v14, v13
	v_div_fmas_f32 v3, v3, v12, v14
	v_div_fixup_f32 v8, v3, v8, v7
	v_pk_mul_f32 v[8:9], v[8:9], v[10:11]
	s_nop 0
	v_cvt_pk_f16_f32 v7, v8, v9
	v_mov_b32_e32 v8, v209
	v_mov_b32_e32 v246, v6
	v_mov_b32_e32 v247, v7
	s_waitcnt vmcnt(5)
	v_cvt_f32_f16_sdwa v3, v110 dst_sel:DWORD dst_unused:UNUSED_PAD src0_sel:WORD_1
	v_ashrrev_i32_e32 v9, 31, v8
	v_lshl_add_u64 v[8:9], v[8:9], 4, s[4:5]
	v_add_co_u32_e32 v8, vcc, s2, v8
	v_cvt_f32_f16_e32 v6, v110
	s_nop 0
	v_addc_co_u32_e32 v9, vcc, 0, v9, vcc
	v_mul_f32_e32 v10, 0xbfb8aa3b, v6
	v_exp_f32_e32 v10, v10
	s_waitcnt vmcnt(4)
; DI unsigned pk2(float a, float b) { f2_t v = {a, b}; bf2_t r = __builtin_convertvector(v, bf2_t); return __builtin_bit_cast(unsigned, r); }
; DI float bflo(unsigned u) { return (float)__builtin_bit_cast(bf2_t, u)[0]; }
; DI float bfhi(unsigned u) { return (float)__builtin_bit_cast(bf2_t, u)[1]; }
; DI float siluf_(float x) { return x / (1.f + __expf(-x)); }
; #define NSA_GATE(c_, nb_) sigmoidf_(bf2f(zb[(size_t)qpos[nb_] * ZS + GATEC + (c_) * 8 + head]))
; DI void nsa_item(const Params& p, int l_, int item, char* lds, int dry) {
;     ...
;     const float lt = l[nb] + shx(l[nb], lane, 32);
;     const float sc = ((lt > 0.f) ? 1.f / lt : 0.f) * NSA_GATE(2, nb);
;     u16* zr = zb + (size_t)qpos[nb] * ZS + GC + head * 64;
; #pragma unroll
;     for (int db = 0; db < 2; ++db)
; #pragma unroll
;       for (int a4 = 0; a4 < 4; ++a4) {
;         uint2* gp = (uint2*)(zr + db * 32 + 8 * a4 + 4 * h);
;         const uint2 gv = *gp;
;         const uint2 pv = *((const uint2*)&scr[((nb * 2 + db) * 2 + (a4 >> 1)) * 256] + (a4 & 1));
;         const unsigned o0 = pv.x, o1 = pv.y;
;         uint2 o;
;         o.x = pk2((bflo(o0) + O[db][nb][4 * a4] * sc) * siluf_(bflo(gv.x)),
;                   (bfhi(o0) + O[db][nb][4 * a4 + 1] * sc) * siluf_(bfhi(gv.x)));
;         o.y = pk2((bflo(o1) + O[db][nb][4 * a4 + 2] * sc) * siluf_(bflo(gv.y)),
;                   (bfhi(o1) + O[db][nb][4 * a4 + 3] * sc) * siluf_(bfhi(gv.y)));
;         if (dry) gp = (uint2*)&scr[((nb * 2 + db) * 2 + (a4 >> 1)) * 256] + (a4 & 1);
;         *gp = o;
;       }
	v_cvt_f32_f16_e32 v12, v112
	v_cvt_f32_f16_sdwa v13, v112 dst_sel:DWORD dst_unused:UNUSED_PAD src0_sel:WORD_1
	v_mul_f32_e32 v8, 0xbfb8aa3b, v3
	v_exp_f32_e32 v11, v8
	v_pk_fma_f32 v[12:13], v[60:61], v[2:3], v[12:13] op_sel_hi:[1,0,1]
	v_pk_add_f32 v[10:11], v[10:11], 1.0 op_sel_hi:[1,0]
	s_nop 0
	v_div_scale_f32 v8, s[0:1], v11, v11, v3
	v_rcp_f32_e32 v14, v8
	s_nop 0
	v_fma_f32 v15, -v8, v14, 1.0
	v_fmac_f32_e32 v14, v15, v14
	v_div_scale_f32 v15, vcc, v3, v11, v3
	v_mul_f32_e32 v48, v15, v14
	v_fma_f32 v49, -v8, v48, v15
	v_fmac_f32_e32 v48, v49, v14
	v_fma_f32 v8, -v8, v48, v15
	v_div_fmas_f32 v8, v8, v14, v48
	v_div_fixup_f32 v11, v8, v11, v3
	v_div_scale_f32 v3, s[0:1], v10, v10, v6
	v_rcp_f32_e32 v8, v3
	s_nop 0
	v_fma_f32 v14, -v3, v8, 1.0
	v_fmac_f32_e32 v8, v14, v8
	v_div_scale_f32 v14, vcc, v6, v10, v6
	v_mul_f32_e32 v15, v14, v8
	v_fma_f32 v48, -v3, v15, v14
	v_fmac_f32_e32 v15, v48, v8
	v_fma_f32 v3, -v3, v15, v14
	v_div_fmas_f32 v3, v3, v8, v15
	v_div_fixup_f32 v10, v3, v10, v6
	v_pk_mul_f32 v[10:11], v[10:11], v[12:13]
	v_cvt_f32_f16_sdwa v12, v111 dst_sel:DWORD dst_unused:UNUSED_PAD src0_sel:WORD_1
	v_cvt_f32_f16_e32 v7, v111
	v_cvt_pk_f16_f32 v6, v10, v11
	v_cvt_f32_f16_e32 v10, v113
	v_cvt_f32_f16_sdwa v11, v113 dst_sel:DWORD dst_unused:UNUSED_PAD src0_sel:WORD_1
	v_mul_f32_e32 v3, 0xbfb8aa3b, v7
	v_mul_f32_e32 v9, 0xbfb8aa3b, v12
	v_exp_f32_e32 v8, v3
	v_exp_f32_e32 v9, v9
	v_pk_fma_f32 v[2:3], v[62:63], v[2:3], v[10:11] op_sel_hi:[1,0,1]
	v_pk_add_f32 v[8:9], v[8:9], 1.0 op_sel_hi:[1,0]
	s_nop 0
	v_div_scale_f32 v10, s[0:1], v9, v9, v12
	v_rcp_f32_e32 v11, v10
	s_nop 0
	v_fma_f32 v13, -v10, v11, 1.0
	v_fmac_f32_e32 v11, v13, v11
	v_div_scale_f32 v13, vcc, v12, v9, v12
	v_mul_f32_e32 v14, v13, v11
	v_fma_f32 v15, -v10, v14, v13
	v_fmac_f32_e32 v14, v15, v11
	v_fma_f32 v10, -v10, v14, v13
	v_div_fmas_f32 v10, v10, v11, v14
	v_div_fixup_f32 v9, v10, v9, v12
	v_div_scale_f32 v10, s[0:1], v8, v8, v7
	v_rcp_f32_e32 v11, v10
	s_nop 0
	v_fma_f32 v12, -v10, v11, 1.0
	v_fmac_f32_e32 v11, v12, v11
	v_div_scale_f32 v12, vcc, v7, v8, v7
	v_mul_f32_e32 v13, v12, v11
	v_fma_f32 v14, -v10, v13, v12
	v_fmac_f32_e32 v13, v14, v11
	v_fma_f32 v10, -v10, v13, v12
	v_div_fmas_f32 v10, v10, v11, v13
	v_div_fixup_f32 v8, v10, v8, v7
	v_pk_mul_f32 v[2:3], v[8:9], v[2:3]
	v_mov_b32_e32 v10, v209
	v_cvt_pk_f16_f32 v7, v2, v3
	ds_bpermute_b32 v2, v176, v164
	v_mov_b32_e32 v248, v6
	v_mov_b32_e32 v249, v7
	s_nop 1
	v_permlane32_swap_b32 v246, v248
	v_permlane32_swap_b32 v247, v249
	global_store_dwordx4 v[232:233], v[246:249], off offset:96
	s_waitcnt lgkmcnt(0)
	v_add_f32_e32 v2, v164, v2
	v_div_scale_f32 v3, s[2:3], v2, v2, 1.0
	v_rcp_f32_e32 v4, v3
	v_cmp_lt_f32_e64 s[0:1], 0, v2
	s_movk_i32 s2, 0x4000
	v_fma_f32 v5, -v3, v4, 1.0
	v_fmac_f32_e32 v4, v5, v4
	v_div_scale_f32 v5, vcc, 1.0, v2, 1.0
	v_mul_f32_e32 v6, v5, v4
	v_fma_f32 v7, -v3, v6, v5
	v_fmac_f32_e32 v6, v7, v4
	v_fma_f32 v3, -v3, v6, v5
	v_div_fmas_f32 v3, v3, v4, v6
	v_div_fixup_f32 v2, v3, v2, 1.0
	global_load_ushort v3, v[170:171], off offset:560
	v_cndmask_b32_e64 v2, 0, v2, s[0:1]
	s_waitcnt vmcnt(0)
	v_cvt_f32_f16_e32 v3, v3
	v_mul_f32_e32 v3, 0xbfb8aa3b, v3
	v_exp_f32_e32 v3, v3
	s_nop 0
	v_add_f32_e32 v3, 1.0, v3
	v_div_scale_f32 v4, s[0:1], v3, v3, 1.0
	v_rcp_f32_e32 v5, v4
	s_nop 0
	v_fma_f32 v6, -v4, v5, 1.0
	v_fmac_f32_e32 v5, v6, v5
	v_div_scale_f32 v6, vcc, 1.0, v3, 1.0
	v_mul_f32_e32 v7, v6, v5
	v_fma_f32 v8, -v4, v7, v6
	v_fmac_f32_e32 v7, v8, v5
	v_fma_f32 v4, -v4, v7, v6
	v_div_fmas_f32 v4, v4, v5, v7
	v_lshl_add_u64 v[6:7], v[168:169], 0, v[0:1]
	v_div_fixup_f32 v3, v4, v3, 1.0
	v_lshl_add_u64 v[4:5], v[6:7], 0, s[8:9]
	v_add_co_u32_e32 v6, vcc, s6, v6
	v_mul_f32_e32 v2, v2, v3
	s_nop 0
	v_addc_co_u32_e32 v7, vcc, 0, v7, vcc
	global_load_dwordx2 v[8:9], v[6:7], off offset:512
	v_mov_b32_e32 v228, v209
	v_ashrrev_i32_e32 v229, 31, v228
	v_lshl_add_u64 v[228:229], v[228:229], 4, s[4:5]
	v_add_co_u32_e32 v230, vcc, 0x4000, v228
	s_nop 1
	v_addc_co_u32_e32 v231, vcc, 0, v229, vcc
	global_load_dwordx2 v[84:85], v[230:231], off
	global_load_dwordx2 v[86:87], v[4:5], off offset:16
	global_load_dwordx2 v[88:89], v[230:231], off offset:8
	global_load_dwordx2 v[90:91], v[4:5], off offset:32
	v_add_co_u32_e32 v230, vcc, 0x5000, v228
	s_nop 1
	v_addc_co_u32_e32 v231, vcc, 0, v229, vcc
	global_load_dwordx2 v[92:93], v[230:231], off
	global_load_dwordx2 v[94:95], v[4:5], off offset:48
	global_load_dwordx2 v[96:97], v[230:231], off offset:8
	global_load_dwordx2 v[98:99], v[4:5], off offset:64
	v_add_co_u32_e32 v230, vcc, 0x6000, v228
	s_nop 1
	v_addc_co_u32_e32 v231, vcc, 0, v229, vcc
	global_load_dwordx2 v[100:101], v[230:231], off
	global_load_dwordx2 v[102:103], v[4:5], off offset:80
	global_load_dwordx2 v[104:105], v[230:231], off offset:8
	global_load_dwordx2 v[106:107], v[4:5], off offset:96
	v_add_co_u32_e32 v230, vcc, 0x7000, v228
	s_nop 1
	v_addc_co_u32_e32 v231, vcc, 0, v229, vcc
	global_load_dwordx2 v[108:109], v[230:231], off
	global_load_dwordx2 v[110:111], v[4:5], off offset:112
	global_load_dwordx2 v[112:113], v[230:231], off offset:8
	v_and_b32_e32 v234, 32, v209
	v_lshrrev_b32_e32 v234, 2, v234
	v_add_co_u32_e32 v232, vcc, v4, v234
	s_nop 1
	v_addc_co_u32_e32 v233, vcc, 0, v5, vcc
	s_waitcnt vmcnt(15)
	v_cvt_f32_f16_e32 v3, v8
	v_ashrrev_i32_e32 v11, 31, v10
	v_lshl_add_u64 v[10:11], v[10:11], 4, s[4:5]
	v_add_co_u32_e32 v10, vcc, s2, v10
	v_cvt_f32_f16_sdwa v0, v8 dst_sel:DWORD dst_unused:UNUSED_PAD src0_sel:WORD_1
	s_nop 0
	v_addc_co_u32_e32 v11, vcc, 0, v11, vcc
	v_mul_f32_e32 v8, 0xbfb8aa3b, v3
	v_exp_f32_e32 v12, v8
	v_mul_f32_e32 v8, 0xbfb8aa3b, v0
	v_exp_f32_e32 v13, v8
	s_waitcnt vmcnt(14)
; DI unsigned pk2(float a, float b) { f2_t v = {a, b}; bf2_t r = __builtin_convertvector(v, bf2_t); return __builtin_bit_cast(unsigned, r); }
; DI float bflo(unsigned u) { return (float)__builtin_bit_cast(bf2_t, u)[0]; }
; DI float bfhi(unsigned u) { return (float)__builtin_bit_cast(bf2_t, u)[1]; }
; DI float siluf_(float x) { return x / (1.f + __expf(-x)); }
; DI void nsa_item(const Params& p, int l_, int item, char* lds, int dry) {
;     ...
; #pragma unroll
;     for (int db = 0; db < 2; ++db)
; #pragma unroll
;       for (int a4 = 0; a4 < 4; ++a4) {
;         uint2* gp = (uint2*)(zr + db * 32 + 8 * a4 + 4 * h);
;         const uint2 gv = *gp;
;         const uint2 pv = *((const uint2*)&scr[((nb * 2 + db) * 2 + (a4 >> 1)) * 256] + (a4 & 1));
;         const unsigned o0 = pv.x, o1 = pv.y;
;         uint2 o;
;         o.x = pk2((bflo(o0) + O[db][nb][4 * a4] * sc) * siluf_(bflo(gv.x)),
;                   (bfhi(o0) + O[db][nb][4 * a4 + 1] * sc) * siluf_(bfhi(gv.x)));
;         o.y = pk2((bflo(o1) + O[db][nb][4 * a4 + 2] * sc) * siluf_(bflo(gv.y)),
;                   (bfhi(o1) + O[db][nb][4 * a4 + 3] * sc) * siluf_(bfhi(gv.y)));
;         if (dry) gp = (uint2*)&scr[((nb * 2 + db) * 2 + (a4 >> 1)) * 256] + (a4 & 1);
;         *gp = o;
;       }
	v_cvt_f32_f16_e32 v14, v84
	v_pk_add_f32 v[12:13], v[12:13], 1.0 op_sel_hi:[1,0]
	v_cvt_f32_f16_sdwa v15, v84 dst_sel:DWORD dst_unused:UNUSED_PAD src0_sel:WORD_1
	v_div_scale_f32 v8, s[0:1], v13, v13, v0
	v_rcp_f32_e32 v10, v8
	v_pk_fma_f32 v[14:15], v[32:33], v[2:3], v[14:15] op_sel_hi:[1,0,1]
	v_fma_f32 v32, -v8, v10, 1.0
	v_fmac_f32_e32 v10, v32, v10
	v_div_scale_f32 v32, vcc, v0, v13, v0
	v_mul_f32_e32 v33, v32, v10
	v_fma_f32 v48, -v8, v33, v32
	v_fmac_f32_e32 v33, v48, v10
	v_fma_f32 v8, -v8, v33, v32
	v_div_fmas_f32 v8, v8, v10, v33
	v_div_fixup_f32 v13, v8, v13, v0
	v_div_scale_f32 v0, s[0:1], v12, v12, v3
	v_rcp_f32_e32 v8, v0
	s_nop 0
	v_fma_f32 v10, -v0, v8, 1.0
	v_fmac_f32_e32 v8, v10, v8
	v_div_scale_f32 v10, vcc, v3, v12, v3
	v_mul_f32_e32 v32, v10, v8
	v_fma_f32 v33, -v0, v32, v10
	v_fmac_f32_e32 v32, v33, v8
	v_fma_f32 v0, -v0, v32, v10
	v_div_fmas_f32 v0, v0, v8, v32
	v_div_fixup_f32 v12, v0, v12, v3
	v_cvt_f32_f16_e32 v3, v9
	v_cvt_f32_f16_sdwa v0, v9 dst_sel:DWORD dst_unused:UNUSED_PAD src0_sel:WORD_1
	v_pk_mul_f32 v[12:13], v[12:13], v[14:15]
	v_mul_f32_e32 v9, 0xbfb8aa3b, v3
	v_exp_f32_e32 v10, v9
	v_mul_f32_e32 v9, 0xbfb8aa3b, v0
	v_cvt_pk_f16_f32 v8, v12, v13
	v_cvt_f32_f16_e32 v12, v85
	v_cvt_f32_f16_sdwa v13, v85 dst_sel:DWORD dst_unused:UNUSED_PAD src0_sel:WORD_1
	v_exp_f32_e32 v11, v9
	v_pk_fma_f32 v[12:13], v[34:35], v[2:3], v[12:13] op_sel_hi:[1,0,1]
	v_pk_add_f32 v[10:11], v[10:11], 1.0 op_sel_hi:[1,0]
	s_nop 0
	v_div_scale_f32 v9, s[0:1], v11, v11, v0
	v_rcp_f32_e32 v14, v9
	s_nop 0
	v_fma_f32 v15, -v9, v14, 1.0
	v_fmac_f32_e32 v14, v15, v14
	v_div_scale_f32 v15, vcc, v0, v11, v0
	v_mul_f32_e32 v32, v15, v14
	v_fma_f32 v33, -v9, v32, v15
	v_fmac_f32_e32 v32, v33, v14
	v_fma_f32 v9, -v9, v32, v15
	v_div_fmas_f32 v9, v9, v14, v32
	v_div_fixup_f32 v11, v9, v11, v0
	v_div_scale_f32 v0, s[0:1], v10, v10, v3
	v_rcp_f32_e32 v9, v0
	s_nop 0
	v_fma_f32 v14, -v0, v9, 1.0
	v_fmac_f32_e32 v9, v14, v9
	v_div_scale_f32 v14, vcc, v3, v10, v3
	v_mul_f32_e32 v15, v14, v9
	v_fma_f32 v32, -v0, v15, v14
	v_fmac_f32_e32 v15, v32, v9
	v_fma_f32 v0, -v0, v15, v14
	v_div_fmas_f32 v0, v0, v9, v15
	v_div_fixup_f32 v10, v0, v10, v3
	v_pk_mul_f32 v[10:11], v[10:11], v[12:13]
	s_nop 0
	v_cvt_pk_f16_f32 v9, v10, v11
	global_store_dwordx2 v[6:7], v[8:9], off offset:512
	v_mov_b32_e32 v8, v209
	s_waitcnt vmcnt(14)
	v_cvt_f32_f16_e32 v3, v86
	v_ashrrev_i32_e32 v9, 31, v8
	v_lshl_add_u64 v[8:9], v[8:9], 4, s[4:5]
	v_add_co_u32_e32 v8, vcc, s2, v8
	v_cvt_f32_f16_sdwa v0, v86 dst_sel:DWORD dst_unused:UNUSED_PAD src0_sel:WORD_1
	s_nop 0
	v_addc_co_u32_e32 v9, vcc, 0, v9, vcc
	v_mul_f32_e32 v6, 0xbfb8aa3b, v3
	v_exp_f32_e32 v10, v6
	v_mul_f32_e32 v6, 0xbfb8aa3b, v0
	v_exp_f32_e32 v11, v6
	s_movk_i32 s2, 0x5000
	v_pk_add_f32 v[10:11], v[10:11], 1.0 op_sel_hi:[1,0]
	s_nop 0
	v_div_scale_f32 v6, s[0:1], v11, v11, v0
	s_waitcnt vmcnt(13)
	v_cvt_f32_f16_e32 v12, v88
	v_cvt_f32_f16_sdwa v13, v88 dst_sel:DWORD dst_unused:UNUSED_PAD src0_sel:WORD_1
	v_rcp_f32_e32 v8, v6
	v_pk_fma_f32 v[12:13], v[36:37], v[2:3], v[12:13] op_sel_hi:[1,0,1]
	v_fma_f32 v14, -v6, v8, 1.0
	v_fmac_f32_e32 v8, v14, v8
	v_div_scale_f32 v14, vcc, v0, v11, v0
	v_mul_f32_e32 v15, v14, v8
	v_fma_f32 v32, -v6, v15, v14
	v_fmac_f32_e32 v15, v32, v8
	v_fma_f32 v6, -v6, v15, v14
	v_div_fmas_f32 v6, v6, v8, v15
	v_div_fixup_f32 v11, v6, v11, v0
	v_div_scale_f32 v0, s[0:1], v10, v10, v3
	v_rcp_f32_e32 v6, v0
	s_nop 0
	v_fma_f32 v8, -v0, v6, 1.0
	v_fmac_f32_e32 v6, v8, v6
	v_div_scale_f32 v8, vcc, v3, v10, v3
	v_mul_f32_e32 v14, v8, v6
	v_fma_f32 v15, -v0, v14, v8
	v_fmac_f32_e32 v14, v15, v6
	v_fma_f32 v0, -v0, v14, v8
	v_div_fmas_f32 v0, v0, v6, v14
	v_div_fixup_f32 v10, v0, v10, v3
	v_cvt_f32_f16_e32 v3, v87
	v_cvt_f32_f16_sdwa v0, v87 dst_sel:DWORD dst_unused:UNUSED_PAD src0_sel:WORD_1
	v_pk_mul_f32 v[10:11], v[10:11], v[12:13]
	v_mul_f32_e32 v7, 0xbfb8aa3b, v3
	v_exp_f32_e32 v8, v7
	v_mul_f32_e32 v7, 0xbfb8aa3b, v0
	v_cvt_pk_f16_f32 v6, v10, v11
	v_cvt_f32_f16_e32 v10, v89
	v_cvt_f32_f16_sdwa v11, v89 dst_sel:DWORD dst_unused:UNUSED_PAD src0_sel:WORD_1
	v_exp_f32_e32 v9, v7
	v_pk_fma_f32 v[10:11], v[38:39], v[2:3], v[10:11] op_sel_hi:[1,0,1]
	v_pk_add_f32 v[8:9], v[8:9], 1.0 op_sel_hi:[1,0]
	s_nop 0
	v_div_scale_f32 v7, s[0:1], v9, v9, v0
	v_rcp_f32_e32 v12, v7
	s_nop 0
	v_fma_f32 v13, -v7, v12, 1.0
	v_fmac_f32_e32 v12, v13, v12
	v_div_scale_f32 v13, vcc, v0, v9, v0
	v_mul_f32_e32 v14, v13, v12
	v_fma_f32 v15, -v7, v14, v13
	v_fmac_f32_e32 v14, v15, v12
	v_fma_f32 v7, -v7, v14, v13
	v_div_fmas_f32 v7, v7, v12, v14
	v_div_fixup_f32 v9, v7, v9, v0
	v_div_scale_f32 v0, s[0:1], v8, v8, v3
	v_rcp_f32_e32 v7, v0
	s_nop 0
	v_fma_f32 v12, -v0, v7, 1.0
	v_fmac_f32_e32 v7, v12, v7
	v_div_scale_f32 v12, vcc, v3, v8, v3
	v_mul_f32_e32 v13, v12, v7
	v_fma_f32 v14, -v0, v13, v12
	v_fmac_f32_e32 v13, v14, v7
	v_fma_f32 v0, -v0, v13, v12
	v_div_fmas_f32 v0, v0, v7, v13
	v_div_fixup_f32 v8, v0, v8, v3
	v_pk_mul_f32 v[8:9], v[8:9], v[10:11]
	s_nop 0
	v_cvt_pk_f16_f32 v7, v8, v9
	global_store_dwordx2 v[4:5], v[6:7], off offset:16
	v_mov_b32_e32 v8, v209
	s_waitcnt vmcnt(13)
	v_cvt_f32_f16_e32 v3, v90
	v_ashrrev_i32_e32 v9, 31, v8
	v_lshl_add_u64 v[8:9], v[8:9], 4, s[4:5]
	v_add_co_u32_e32 v8, vcc, s2, v8
	v_cvt_f32_f16_sdwa v0, v90 dst_sel:DWORD dst_unused:UNUSED_PAD src0_sel:WORD_1
	s_nop 0
	v_addc_co_u32_e32 v9, vcc, 0, v9, vcc
	v_mul_f32_e32 v6, 0xbfb8aa3b, v3
	v_exp_f32_e32 v10, v6
	v_mul_f32_e32 v6, 0xbfb8aa3b, v0
	v_exp_f32_e32 v11, v6
	s_waitcnt vmcnt(12)
; DI unsigned pk2(float a, float b) { f2_t v = {a, b}; bf2_t r = __builtin_convertvector(v, bf2_t); return __builtin_bit_cast(unsigned, r); }
; DI float bflo(unsigned u) { return (float)__builtin_bit_cast(bf2_t, u)[0]; }
; DI float bfhi(unsigned u) { return (float)__builtin_bit_cast(bf2_t, u)[1]; }
; DI float siluf_(float x) { return x / (1.f + __expf(-x)); }
; DI void nsa_item(const Params& p, int l_, int item, char* lds, int dry) {
;     ...
; #pragma unroll
;     for (int db = 0; db < 2; ++db)
; #pragma unroll
;       for (int a4 = 0; a4 < 4; ++a4) {
;         uint2* gp = (uint2*)(zr + db * 32 + 8 * a4 + 4 * h);
;         const uint2 gv = *gp;
;         const uint2 pv = *((const uint2*)&scr[((nb * 2 + db) * 2 + (a4 >> 1)) * 256] + (a4 & 1));
;         const unsigned o0 = pv.x, o1 = pv.y;
;         uint2 o;
;         o.x = pk2((bflo(o0) + O[db][nb][4 * a4] * sc) * siluf_(bflo(gv.x)),
;                   (bfhi(o0) + O[db][nb][4 * a4 + 1] * sc) * siluf_(bfhi(gv.x)));
;         o.y = pk2((bflo(o1) + O[db][nb][4 * a4 + 2] * sc) * siluf_(bflo(gv.y)),
;                   (bfhi(o1) + O[db][nb][4 * a4 + 3] * sc) * siluf_(bfhi(gv.y)));
;         if (dry) gp = (uint2*)&scr[((nb * 2 + db) * 2 + (a4 >> 1)) * 256] + (a4 & 1);
;         *gp = o;
;       }
	v_cvt_f32_f16_e32 v12, v92
	v_pk_add_f32 v[10:11], v[10:11], 1.0 op_sel_hi:[1,0]
	v_cvt_f32_f16_sdwa v13, v92 dst_sel:DWORD dst_unused:UNUSED_PAD src0_sel:WORD_1
	v_div_scale_f32 v6, s[0:1], v11, v11, v0
	v_rcp_f32_e32 v8, v6
	v_pk_fma_f32 v[12:13], v[40:41], v[2:3], v[12:13] op_sel_hi:[1,0,1]
	v_fma_f32 v14, -v6, v8, 1.0
	v_fmac_f32_e32 v8, v14, v8
	v_div_scale_f32 v14, vcc, v0, v11, v0
	v_mul_f32_e32 v15, v14, v8
	v_fma_f32 v32, -v6, v15, v14
	v_fmac_f32_e32 v15, v32, v8
	v_fma_f32 v6, -v6, v15, v14
	v_div_fmas_f32 v6, v6, v8, v15
	v_div_fixup_f32 v11, v6, v11, v0
	v_div_scale_f32 v0, s[0:1], v10, v10, v3
	v_rcp_f32_e32 v6, v0
	s_nop 0
	v_fma_f32 v8, -v0, v6, 1.0
	v_fmac_f32_e32 v6, v8, v6
	v_div_scale_f32 v8, vcc, v3, v10, v3
	v_mul_f32_e32 v14, v8, v6
	v_fma_f32 v15, -v0, v14, v8
	v_fmac_f32_e32 v14, v15, v6
	v_fma_f32 v0, -v0, v14, v8
	v_div_fmas_f32 v0, v0, v6, v14
	v_div_fixup_f32 v10, v0, v10, v3
	v_cvt_f32_f16_e32 v3, v91
	v_cvt_f32_f16_sdwa v0, v91 dst_sel:DWORD dst_unused:UNUSED_PAD src0_sel:WORD_1
	v_pk_mul_f32 v[10:11], v[10:11], v[12:13]
	v_mul_f32_e32 v7, 0xbfb8aa3b, v3
	v_exp_f32_e32 v8, v7
	v_mul_f32_e32 v7, 0xbfb8aa3b, v0
	v_cvt_pk_f16_f32 v6, v10, v11
	v_cvt_f32_f16_e32 v10, v93
	v_cvt_f32_f16_sdwa v11, v93 dst_sel:DWORD dst_unused:UNUSED_PAD src0_sel:WORD_1
	v_exp_f32_e32 v9, v7
	v_pk_fma_f32 v[10:11], v[42:43], v[2:3], v[10:11] op_sel_hi:[1,0,1]
	v_pk_add_f32 v[8:9], v[8:9], 1.0 op_sel_hi:[1,0]
	s_nop 0
	v_div_scale_f32 v7, s[0:1], v9, v9, v0
	v_rcp_f32_e32 v12, v7
	s_nop 0
	v_fma_f32 v13, -v7, v12, 1.0
	v_fmac_f32_e32 v12, v13, v12
	v_div_scale_f32 v13, vcc, v0, v9, v0
	v_mul_f32_e32 v14, v13, v12
	v_fma_f32 v15, -v7, v14, v13
	v_fmac_f32_e32 v14, v15, v12
	v_fma_f32 v7, -v7, v14, v13
	v_div_fmas_f32 v7, v7, v12, v14
	v_div_fixup_f32 v9, v7, v9, v0
	v_div_scale_f32 v0, s[0:1], v8, v8, v3
	v_rcp_f32_e32 v7, v0
	s_nop 0
	v_fma_f32 v12, -v0, v7, 1.0
	v_fmac_f32_e32 v7, v12, v7
	v_div_scale_f32 v12, vcc, v3, v8, v3
	v_mul_f32_e32 v13, v12, v7
	v_fma_f32 v14, -v0, v13, v12
	v_fmac_f32_e32 v13, v14, v7
	v_fma_f32 v0, -v0, v13, v12
	v_div_fmas_f32 v0, v0, v7, v13
	v_div_fixup_f32 v8, v0, v8, v3
	v_pk_mul_f32 v[8:9], v[8:9], v[10:11]
	s_nop 0
	v_cvt_pk_f16_f32 v7, v8, v9
	v_mov_b32_e32 v246, v6
	v_mov_b32_e32 v247, v7
	v_mov_b32_e32 v8, v209
	s_waitcnt vmcnt(11)
	v_cvt_f32_f16_e32 v3, v94
	v_ashrrev_i32_e32 v9, 31, v8
	v_lshl_add_u64 v[8:9], v[8:9], 4, s[4:5]
	v_add_co_u32_e32 v8, vcc, s2, v8
	v_cvt_f32_f16_sdwa v0, v94 dst_sel:DWORD dst_unused:UNUSED_PAD src0_sel:WORD_1
	s_nop 0
	v_addc_co_u32_e32 v9, vcc, 0, v9, vcc
	v_mul_f32_e32 v6, 0xbfb8aa3b, v3
	v_exp_f32_e32 v10, v6
	v_mul_f32_e32 v6, 0xbfb8aa3b, v0
	v_exp_f32_e32 v11, v6
	s_movk_i32 s2, 0x6000
	v_pk_add_f32 v[10:11], v[10:11], 1.0 op_sel_hi:[1,0]
	s_nop 0
	v_div_scale_f32 v6, s[0:1], v11, v11, v0
	s_waitcnt vmcnt(10)
	v_cvt_f32_f16_e32 v12, v96
	v_cvt_f32_f16_sdwa v13, v96 dst_sel:DWORD dst_unused:UNUSED_PAD src0_sel:WORD_1
	v_rcp_f32_e32 v8, v6
	v_pk_fma_f32 v[12:13], v[44:45], v[2:3], v[12:13] op_sel_hi:[1,0,1]
	v_fma_f32 v14, -v6, v8, 1.0
	v_fmac_f32_e32 v8, v14, v8
	v_div_scale_f32 v14, vcc, v0, v11, v0
	v_mul_f32_e32 v15, v14, v8
	v_fma_f32 v32, -v6, v15, v14
	v_fmac_f32_e32 v15, v32, v8
	v_fma_f32 v6, -v6, v15, v14
	v_div_fmas_f32 v6, v6, v8, v15
	v_div_fixup_f32 v11, v6, v11, v0
	v_div_scale_f32 v0, s[0:1], v10, v10, v3
	v_rcp_f32_e32 v6, v0
	s_nop 0
	v_fma_f32 v8, -v0, v6, 1.0
	v_fmac_f32_e32 v6, v8, v6
	v_div_scale_f32 v8, vcc, v3, v10, v3
	v_mul_f32_e32 v14, v8, v6
	v_fma_f32 v15, -v0, v14, v8
	v_fmac_f32_e32 v14, v15, v6
	v_fma_f32 v0, -v0, v14, v8
	v_div_fmas_f32 v0, v0, v6, v14
	v_div_fixup_f32 v10, v0, v10, v3
	v_cvt_f32_f16_e32 v3, v95
	v_cvt_f32_f16_sdwa v0, v95 dst_sel:DWORD dst_unused:UNUSED_PAD src0_sel:WORD_1
	v_pk_mul_f32 v[10:11], v[10:11], v[12:13]
	v_mul_f32_e32 v7, 0xbfb8aa3b, v3
	v_exp_f32_e32 v8, v7
	v_mul_f32_e32 v7, 0xbfb8aa3b, v0
	v_cvt_pk_f16_f32 v6, v10, v11
	v_cvt_f32_f16_e32 v10, v97
	v_cvt_f32_f16_sdwa v11, v97 dst_sel:DWORD dst_unused:UNUSED_PAD src0_sel:WORD_1
	v_exp_f32_e32 v9, v7
	v_pk_fma_f32 v[10:11], v[46:47], v[2:3], v[10:11] op_sel_hi:[1,0,1]
	v_pk_add_f32 v[8:9], v[8:9], 1.0 op_sel_hi:[1,0]
	s_nop 0
	v_div_scale_f32 v7, s[0:1], v9, v9, v0
	v_rcp_f32_e32 v12, v7
	s_nop 0
	v_fma_f32 v13, -v7, v12, 1.0
	v_fmac_f32_e32 v12, v13, v12
	v_div_scale_f32 v13, vcc, v0, v9, v0
	v_mul_f32_e32 v14, v13, v12
	v_fma_f32 v15, -v7, v14, v13
	v_fmac_f32_e32 v14, v15, v12
	v_fma_f32 v7, -v7, v14, v13
	v_div_fmas_f32 v7, v7, v12, v14
	v_div_fixup_f32 v9, v7, v9, v0
	v_div_scale_f32 v0, s[0:1], v8, v8, v3
	v_rcp_f32_e32 v7, v0
	s_nop 0
	v_fma_f32 v12, -v0, v7, 1.0
	v_fmac_f32_e32 v7, v12, v7
	v_div_scale_f32 v12, vcc, v3, v8, v3
	v_mul_f32_e32 v13, v12, v7
	v_fma_f32 v14, -v0, v13, v12
	v_fmac_f32_e32 v13, v14, v7
	v_fma_f32 v0, -v0, v13, v12
	v_div_fmas_f32 v0, v0, v7, v13
	v_div_fixup_f32 v8, v0, v8, v3
	v_pk_mul_f32 v[8:9], v[8:9], v[10:11]
	s_nop 0
	v_cvt_pk_f16_f32 v7, v8, v9
	v_mov_b32_e32 v248, v6
	v_mov_b32_e32 v249, v7
	s_nop 1
	v_permlane32_swap_b32 v246, v248
	v_permlane32_swap_b32 v247, v249
	global_store_dwordx4 v[232:233], v[246:249], off offset:32
	v_mov_b32_e32 v8, v209
	s_waitcnt vmcnt(10)
	v_cvt_f32_f16_e32 v3, v98
	v_ashrrev_i32_e32 v9, 31, v8
	v_lshl_add_u64 v[8:9], v[8:9], 4, s[4:5]
	v_add_co_u32_e32 v8, vcc, s2, v8
	v_cvt_f32_f16_sdwa v0, v98 dst_sel:DWORD dst_unused:UNUSED_PAD src0_sel:WORD_1
	s_nop 0
	v_addc_co_u32_e32 v9, vcc, 0, v9, vcc
	v_mul_f32_e32 v6, 0xbfb8aa3b, v3
	v_exp_f32_e32 v10, v6
	v_mul_f32_e32 v6, 0xbfb8aa3b, v0
	v_exp_f32_e32 v11, v6
	s_waitcnt vmcnt(9)
; DI unsigned pk2(float a, float b) { f2_t v = {a, b}; bf2_t r = __builtin_convertvector(v, bf2_t); return __builtin_bit_cast(unsigned, r); }
; DI float bflo(unsigned u) { return (float)__builtin_bit_cast(bf2_t, u)[0]; }
; DI float bfhi(unsigned u) { return (float)__builtin_bit_cast(bf2_t, u)[1]; }
; DI float siluf_(float x) { return x / (1.f + __expf(-x)); }
; DI void nsa_item(const Params& p, int l_, int item, char* lds, int dry) {
;     ...
; #pragma unroll
;     for (int db = 0; db < 2; ++db)
; #pragma unroll
;       for (int a4 = 0; a4 < 4; ++a4) {
;         uint2* gp = (uint2*)(zr + db * 32 + 8 * a4 + 4 * h);
;         const uint2 gv = *gp;
;         const uint2 pv = *((const uint2*)&scr[((nb * 2 + db) * 2 + (a4 >> 1)) * 256] + (a4 & 1));
;         const unsigned o0 = pv.x, o1 = pv.y;
;         uint2 o;
;         o.x = pk2((bflo(o0) + O[db][nb][4 * a4] * sc) * siluf_(bflo(gv.x)),
;                   (bfhi(o0) + O[db][nb][4 * a4 + 1] * sc) * siluf_(bfhi(gv.x)));
;         o.y = pk2((bflo(o1) + O[db][nb][4 * a4 + 2] * sc) * siluf_(bflo(gv.y)),
;                   (bfhi(o1) + O[db][nb][4 * a4 + 3] * sc) * siluf_(bfhi(gv.y)));
;         if (dry) gp = (uint2*)&scr[((nb * 2 + db) * 2 + (a4 >> 1)) * 256] + (a4 & 1);
;         *gp = o;
;       }
	v_cvt_f32_f16_e32 v12, v100
	v_pk_add_f32 v[10:11], v[10:11], 1.0 op_sel_hi:[1,0]
	v_cvt_f32_f16_sdwa v13, v100 dst_sel:DWORD dst_unused:UNUSED_PAD src0_sel:WORD_1
	v_div_scale_f32 v6, s[0:1], v11, v11, v0
	v_rcp_f32_e32 v8, v6
	v_pk_fma_f32 v[12:13], v[16:17], v[2:3], v[12:13] op_sel_hi:[1,0,1]
	v_fma_f32 v14, -v6, v8, 1.0
	v_fmac_f32_e32 v8, v14, v8
	v_div_scale_f32 v14, vcc, v0, v11, v0
	v_mul_f32_e32 v15, v14, v8
	v_fma_f32 v16, -v6, v15, v14
	v_fmac_f32_e32 v15, v16, v8
	v_fma_f32 v6, -v6, v15, v14
	v_div_fmas_f32 v6, v6, v8, v15
	v_div_fixup_f32 v11, v6, v11, v0
	v_div_scale_f32 v0, s[0:1], v10, v10, v3
	v_rcp_f32_e32 v6, v0
	s_nop 0
	v_fma_f32 v8, -v0, v6, 1.0
	v_fmac_f32_e32 v6, v8, v6
	v_div_scale_f32 v8, vcc, v3, v10, v3
	v_mul_f32_e32 v14, v8, v6
	v_fma_f32 v15, -v0, v14, v8
	v_fmac_f32_e32 v14, v15, v6
	v_fma_f32 v0, -v0, v14, v8
	v_div_fmas_f32 v0, v0, v6, v14
	v_div_fixup_f32 v10, v0, v10, v3
	v_cvt_f32_f16_e32 v3, v99
	v_cvt_f32_f16_sdwa v0, v99 dst_sel:DWORD dst_unused:UNUSED_PAD src0_sel:WORD_1
	v_pk_mul_f32 v[10:11], v[10:11], v[12:13]
	v_mul_f32_e32 v7, 0xbfb8aa3b, v3
	v_exp_f32_e32 v8, v7
	v_mul_f32_e32 v7, 0xbfb8aa3b, v0
	v_cvt_pk_f16_f32 v6, v10, v11
	v_cvt_f32_f16_e32 v10, v101
	v_cvt_f32_f16_sdwa v11, v101 dst_sel:DWORD dst_unused:UNUSED_PAD src0_sel:WORD_1
	v_exp_f32_e32 v9, v7
	v_pk_fma_f32 v[10:11], v[18:19], v[2:3], v[10:11] op_sel_hi:[1,0,1]
	v_pk_add_f32 v[8:9], v[8:9], 1.0 op_sel_hi:[1,0]
	s_nop 0
	v_div_scale_f32 v7, s[0:1], v9, v9, v0
	v_rcp_f32_e32 v12, v7
	s_nop 0
	v_fma_f32 v13, -v7, v12, 1.0
	v_fmac_f32_e32 v12, v13, v12
	v_div_scale_f32 v13, vcc, v0, v9, v0
	v_mul_f32_e32 v14, v13, v12
	v_fma_f32 v15, -v7, v14, v13
	v_fmac_f32_e32 v14, v15, v12
	v_fma_f32 v7, -v7, v14, v13
	v_div_fmas_f32 v7, v7, v12, v14
	v_div_fixup_f32 v9, v7, v9, v0
	v_div_scale_f32 v0, s[0:1], v8, v8, v3
	v_rcp_f32_e32 v7, v0
	s_nop 0
	v_fma_f32 v12, -v0, v7, 1.0
	v_fmac_f32_e32 v7, v12, v7
	v_div_scale_f32 v12, vcc, v3, v8, v3
	v_mul_f32_e32 v13, v12, v7
	v_fma_f32 v14, -v0, v13, v12
	v_fmac_f32_e32 v13, v14, v7
	v_fma_f32 v0, -v0, v13, v12
	v_div_fmas_f32 v0, v0, v7, v13
	v_div_fixup_f32 v8, v0, v8, v3
	v_pk_mul_f32 v[8:9], v[8:9], v[10:11]
	s_nop 0
	v_cvt_pk_f16_f32 v7, v8, v9
	v_mov_b32_e32 v246, v6
	v_mov_b32_e32 v247, v7
	v_mov_b32_e32 v8, v209
	s_waitcnt vmcnt(8)
	v_cvt_f32_f16_e32 v3, v102
	v_ashrrev_i32_e32 v9, 31, v8
	v_lshl_add_u64 v[8:9], v[8:9], 4, s[4:5]
	v_add_co_u32_e32 v8, vcc, s2, v8
	v_cvt_f32_f16_sdwa v0, v102 dst_sel:DWORD dst_unused:UNUSED_PAD src0_sel:WORD_1
	s_nop 0
	v_addc_co_u32_e32 v9, vcc, 0, v9, vcc
	v_mul_f32_e32 v6, 0xbfb8aa3b, v3
	v_exp_f32_e32 v10, v6
	v_mul_f32_e32 v6, 0xbfb8aa3b, v0
	v_exp_f32_e32 v11, v6
	s_movk_i32 s2, 0x7000
	v_pk_add_f32 v[10:11], v[10:11], 1.0 op_sel_hi:[1,0]
	s_nop 0
	v_div_scale_f32 v6, s[0:1], v11, v11, v0
	s_waitcnt vmcnt(7)
	v_cvt_f32_f16_e32 v12, v104
	v_cvt_f32_f16_sdwa v13, v104 dst_sel:DWORD dst_unused:UNUSED_PAD src0_sel:WORD_1
	v_rcp_f32_e32 v8, v6
	v_pk_fma_f32 v[12:13], v[20:21], v[2:3], v[12:13] op_sel_hi:[1,0,1]
	v_fma_f32 v14, -v6, v8, 1.0
	v_fmac_f32_e32 v8, v14, v8
	v_div_scale_f32 v14, vcc, v0, v11, v0
	v_mul_f32_e32 v15, v14, v8
	v_fma_f32 v16, -v6, v15, v14
	v_fmac_f32_e32 v15, v16, v8
	v_fma_f32 v6, -v6, v15, v14
	v_div_fmas_f32 v6, v6, v8, v15
	v_div_fixup_f32 v11, v6, v11, v0
	v_div_scale_f32 v0, s[0:1], v10, v10, v3
	v_rcp_f32_e32 v6, v0
	s_nop 0
	v_fma_f32 v8, -v0, v6, 1.0
	v_fmac_f32_e32 v6, v8, v6
	v_div_scale_f32 v8, vcc, v3, v10, v3
	v_mul_f32_e32 v14, v8, v6
	v_fma_f32 v15, -v0, v14, v8
	v_fmac_f32_e32 v14, v15, v6
	v_fma_f32 v0, -v0, v14, v8
	v_div_fmas_f32 v0, v0, v6, v14
	v_div_fixup_f32 v10, v0, v10, v3
	v_cvt_f32_f16_e32 v3, v103
	v_cvt_f32_f16_sdwa v0, v103 dst_sel:DWORD dst_unused:UNUSED_PAD src0_sel:WORD_1
	v_pk_mul_f32 v[10:11], v[10:11], v[12:13]
	v_mul_f32_e32 v7, 0xbfb8aa3b, v3
	v_exp_f32_e32 v8, v7
	v_mul_f32_e32 v7, 0xbfb8aa3b, v0
	v_cvt_pk_f16_f32 v6, v10, v11
	v_cvt_f32_f16_e32 v10, v105
	v_cvt_f32_f16_sdwa v11, v105 dst_sel:DWORD dst_unused:UNUSED_PAD src0_sel:WORD_1
	v_exp_f32_e32 v9, v7
	v_pk_fma_f32 v[10:11], v[22:23], v[2:3], v[10:11] op_sel_hi:[1,0,1]
	v_pk_add_f32 v[8:9], v[8:9], 1.0 op_sel_hi:[1,0]
	s_nop 0
	v_div_scale_f32 v7, s[0:1], v9, v9, v0
	v_rcp_f32_e32 v12, v7
	s_nop 0
	v_fma_f32 v13, -v7, v12, 1.0
	v_fmac_f32_e32 v12, v13, v12
	v_div_scale_f32 v13, vcc, v0, v9, v0
	v_mul_f32_e32 v14, v13, v12
	v_fma_f32 v15, -v7, v14, v13
	v_fmac_f32_e32 v14, v15, v12
	v_fma_f32 v7, -v7, v14, v13
	v_div_fmas_f32 v7, v7, v12, v14
	v_div_fixup_f32 v9, v7, v9, v0
	v_div_scale_f32 v0, s[0:1], v8, v8, v3
	v_rcp_f32_e32 v7, v0
	s_nop 0
	v_fma_f32 v12, -v0, v7, 1.0
	v_fmac_f32_e32 v7, v12, v7
	v_div_scale_f32 v12, vcc, v3, v8, v3
	v_mul_f32_e32 v13, v12, v7
	v_fma_f32 v14, -v0, v13, v12
	v_fmac_f32_e32 v13, v14, v7
	v_fma_f32 v0, -v0, v13, v12
	v_div_fmas_f32 v0, v0, v7, v13
	v_div_fixup_f32 v8, v0, v8, v3
	v_pk_mul_f32 v[8:9], v[8:9], v[10:11]
	s_nop 0
	v_cvt_pk_f16_f32 v7, v8, v9
	v_mov_b32_e32 v248, v6
	v_mov_b32_e32 v249, v7
	s_nop 1
	v_permlane32_swap_b32 v246, v248
	v_permlane32_swap_b32 v247, v249
	global_store_dwordx4 v[232:233], v[246:249], off offset:64
	v_mov_b32_e32 v8, v209
	s_waitcnt vmcnt(7)
; DI unsigned pk2(float a, float b) { f2_t v = {a, b}; bf2_t r = __builtin_convertvector(v, bf2_t); return __builtin_bit_cast(unsigned, r); }
; DI float bflo(unsigned u) { return (float)__builtin_bit_cast(bf2_t, u)[0]; }
; DI float bfhi(unsigned u) { return (float)__builtin_bit_cast(bf2_t, u)[1]; }
; DI float siluf_(float x) { return x / (1.f + __expf(-x)); }
; DI void nsa_item(const Params& p, int l_, int item, char* lds, int dry) {
;     ...
; #pragma unroll
;     for (int db = 0; db < 2; ++db)
; #pragma unroll
;       for (int a4 = 0; a4 < 4; ++a4) {
;         uint2* gp = (uint2*)(zr + db * 32 + 8 * a4 + 4 * h);
;         const uint2 gv = *gp;
;         const uint2 pv = *((const uint2*)&scr[((nb * 2 + db) * 2 + (a4 >> 1)) * 256] + (a4 & 1));
;         const unsigned o0 = pv.x, o1 = pv.y;
;         uint2 o;
;         o.x = pk2((bflo(o0) + O[db][nb][4 * a4] * sc) * siluf_(bflo(gv.x)),
;                   (bfhi(o0) + O[db][nb][4 * a4 + 1] * sc) * siluf_(bfhi(gv.x)));
;         o.y = pk2((bflo(o1) + O[db][nb][4 * a4 + 2] * sc) * siluf_(bflo(gv.y)),
;                   (bfhi(o1) + O[db][nb][4 * a4 + 3] * sc) * siluf_(bfhi(gv.y)));
;         if (dry) gp = (uint2*)&scr[((nb * 2 + db) * 2 + (a4 >> 1)) * 256] + (a4 & 1);
;         *gp = o;
;       }
;   }
	v_cvt_f32_f16_e32 v3, v106
	v_ashrrev_i32_e32 v9, 31, v8
	v_lshl_add_u64 v[8:9], v[8:9], 4, s[4:5]
	v_add_co_u32_e32 v8, vcc, s2, v8
	v_cvt_f32_f16_sdwa v0, v106 dst_sel:DWORD dst_unused:UNUSED_PAD src0_sel:WORD_1
	s_nop 0
	v_addc_co_u32_e32 v9, vcc, 0, v9, vcc
	v_mul_f32_e32 v6, 0xbfb8aa3b, v3
	v_exp_f32_e32 v10, v6
	v_mul_f32_e32 v6, 0xbfb8aa3b, v0
	v_exp_f32_e32 v11, v6
	s_waitcnt vmcnt(6)
	v_cvt_f32_f16_e32 v12, v108
	v_pk_add_f32 v[10:11], v[10:11], 1.0 op_sel_hi:[1,0]
	v_cvt_f32_f16_sdwa v13, v108 dst_sel:DWORD dst_unused:UNUSED_PAD src0_sel:WORD_1
	v_div_scale_f32 v6, s[0:1], v11, v11, v0
	v_rcp_f32_e32 v8, v6
	v_pk_fma_f32 v[12:13], v[24:25], v[2:3], v[12:13] op_sel_hi:[1,0,1]
	v_fma_f32 v14, -v6, v8, 1.0
	v_fmac_f32_e32 v8, v14, v8
	v_div_scale_f32 v14, vcc, v0, v11, v0
	v_mul_f32_e32 v15, v14, v8
	v_fma_f32 v16, -v6, v15, v14
	v_fmac_f32_e32 v15, v16, v8
	v_fma_f32 v6, -v6, v15, v14
	v_div_fmas_f32 v6, v6, v8, v15
	v_div_fixup_f32 v11, v6, v11, v0
	v_div_scale_f32 v0, s[0:1], v10, v10, v3
	v_rcp_f32_e32 v6, v0
	s_nop 0
	v_fma_f32 v8, -v0, v6, 1.0
	v_fmac_f32_e32 v6, v8, v6
	v_div_scale_f32 v8, vcc, v3, v10, v3
	v_mul_f32_e32 v14, v8, v6
	v_fma_f32 v15, -v0, v14, v8
	v_fmac_f32_e32 v14, v15, v6
	v_fma_f32 v0, -v0, v14, v8
	v_div_fmas_f32 v0, v0, v6, v14
	v_div_fixup_f32 v10, v0, v10, v3
	v_cvt_f32_f16_e32 v3, v107
	v_cvt_f32_f16_sdwa v0, v107 dst_sel:DWORD dst_unused:UNUSED_PAD src0_sel:WORD_1
	v_pk_mul_f32 v[10:11], v[10:11], v[12:13]
	v_mul_f32_e32 v7, 0xbfb8aa3b, v3
	v_exp_f32_e32 v8, v7
	v_mul_f32_e32 v7, 0xbfb8aa3b, v0
	v_cvt_pk_f16_f32 v6, v10, v11
	v_cvt_f32_f16_e32 v10, v109
	v_cvt_f32_f16_sdwa v11, v109 dst_sel:DWORD dst_unused:UNUSED_PAD src0_sel:WORD_1
	v_exp_f32_e32 v9, v7
	v_pk_fma_f32 v[10:11], v[26:27], v[2:3], v[10:11] op_sel_hi:[1,0,1]
	v_pk_add_f32 v[8:9], v[8:9], 1.0 op_sel_hi:[1,0]
	s_nop 0
	v_div_scale_f32 v7, s[0:1], v9, v9, v0
	v_rcp_f32_e32 v12, v7
	s_nop 0
	v_fma_f32 v13, -v7, v12, 1.0
	v_fmac_f32_e32 v12, v13, v12
	v_div_scale_f32 v13, vcc, v0, v9, v0
	v_mul_f32_e32 v14, v13, v12
	v_fma_f32 v15, -v7, v14, v13
	v_fmac_f32_e32 v14, v15, v12
	v_fma_f32 v7, -v7, v14, v13
	v_div_fmas_f32 v7, v7, v12, v14
	v_div_fixup_f32 v9, v7, v9, v0
	v_div_scale_f32 v0, s[0:1], v8, v8, v3
	v_rcp_f32_e32 v7, v0
	s_nop 0
	v_fma_f32 v12, -v0, v7, 1.0
	v_fmac_f32_e32 v7, v12, v7
	v_div_scale_f32 v12, vcc, v3, v8, v3
	v_mul_f32_e32 v13, v12, v7
	v_fma_f32 v14, -v0, v13, v12
	v_fmac_f32_e32 v13, v14, v7
	v_fma_f32 v0, -v0, v13, v12
	v_div_fmas_f32 v0, v0, v7, v13
	v_div_fixup_f32 v8, v0, v8, v3
	v_pk_mul_f32 v[8:9], v[8:9], v[10:11]
	s_nop 0
	v_cvt_pk_f16_f32 v7, v8, v9
	v_mov_b32_e32 v246, v6
	v_mov_b32_e32 v247, v7
	v_mov_b32_e32 v8, v209
	s_waitcnt vmcnt(5)
	v_cvt_f32_f16_e32 v3, v110
	v_ashrrev_i32_e32 v9, 31, v8
	v_lshl_add_u64 v[8:9], v[8:9], 4, s[4:5]
	v_add_co_u32_e32 v8, vcc, s2, v8
	v_cvt_f32_f16_sdwa v0, v110 dst_sel:DWORD dst_unused:UNUSED_PAD src0_sel:WORD_1
	s_nop 0
	v_addc_co_u32_e32 v9, vcc, 0, v9, vcc
	v_mul_f32_e32 v6, 0xbfb8aa3b, v3
	v_exp_f32_e32 v10, v6
	v_mul_f32_e32 v6, 0xbfb8aa3b, v0
	v_exp_f32_e32 v11, v6
	s_waitcnt vmcnt(4)
	v_cvt_f32_f16_e32 v12, v112
	v_pk_add_f32 v[10:11], v[10:11], 1.0 op_sel_hi:[1,0]
	v_cvt_f32_f16_sdwa v13, v112 dst_sel:DWORD dst_unused:UNUSED_PAD src0_sel:WORD_1
	v_div_scale_f32 v6, s[0:1], v11, v11, v0
	v_rcp_f32_e32 v8, v6
	v_pk_fma_f32 v[12:13], v[28:29], v[2:3], v[12:13] op_sel_hi:[1,0,1]
	v_fma_f32 v14, -v6, v8, 1.0
	v_fmac_f32_e32 v8, v14, v8
	v_div_scale_f32 v14, vcc, v0, v11, v0
	v_mul_f32_e32 v15, v14, v8
	v_fma_f32 v16, -v6, v15, v14
	v_fmac_f32_e32 v15, v16, v8
	v_fma_f32 v6, -v6, v15, v14
	v_div_fmas_f32 v6, v6, v8, v15
	v_div_fixup_f32 v11, v6, v11, v0
	v_div_scale_f32 v0, s[0:1], v10, v10, v3
	v_rcp_f32_e32 v6, v0
	s_nop 0
	v_fma_f32 v8, -v0, v6, 1.0
	v_fmac_f32_e32 v6, v8, v6
	v_div_scale_f32 v8, vcc, v3, v10, v3
	v_mul_f32_e32 v14, v8, v6
	v_fma_f32 v15, -v0, v14, v8
	v_fmac_f32_e32 v14, v15, v6
	v_fma_f32 v0, -v0, v14, v8
	v_div_fmas_f32 v0, v0, v6, v14
	v_div_fixup_f32 v10, v0, v10, v3
	v_cvt_f32_f16_sdwa v0, v111 dst_sel:DWORD dst_unused:UNUSED_PAD src0_sel:WORD_1
	v_cvt_f32_f16_e32 v7, v111
	v_pk_mul_f32 v[10:11], v[10:11], v[12:13]
	v_mul_f32_e32 v3, 0xbfb8aa3b, v7
	v_cvt_pk_f16_f32 v6, v10, v11
	v_cvt_f32_f16_e32 v10, v113
	v_cvt_f32_f16_sdwa v11, v113 dst_sel:DWORD dst_unused:UNUSED_PAD src0_sel:WORD_1
	v_mul_f32_e32 v9, 0xbfb8aa3b, v0
	v_exp_f32_e32 v8, v3
	v_exp_f32_e32 v9, v9
	v_pk_fma_f32 v[2:3], v[30:31], v[2:3], v[10:11] op_sel_hi:[1,0,1]
	v_pk_add_f32 v[8:9], v[8:9], 1.0 op_sel_hi:[1,0]
	s_nop 0
	v_div_scale_f32 v10, s[0:1], v9, v9, v0
	v_rcp_f32_e32 v11, v10
	s_nop 0
	v_fma_f32 v12, -v10, v11, 1.0
	v_fmac_f32_e32 v11, v12, v11
	v_div_scale_f32 v12, vcc, v0, v9, v0
	v_mul_f32_e32 v13, v12, v11
	v_fma_f32 v14, -v10, v13, v12
	v_fmac_f32_e32 v13, v14, v11
	v_fma_f32 v10, -v10, v13, v12
	v_div_fmas_f32 v10, v10, v11, v13
	v_div_fixup_f32 v9, v10, v9, v0
	v_div_scale_f32 v0, s[0:1], v8, v8, v7
	v_rcp_f32_e32 v10, v0
	s_mov_b64 s[0:1], 0
	v_fma_f32 v11, -v0, v10, 1.0
	v_fmac_f32_e32 v10, v11, v10
	v_div_scale_f32 v11, vcc, v7, v8, v7
	v_mul_f32_e32 v12, v11, v10
	v_fma_f32 v13, -v0, v12, v11
	v_fmac_f32_e32 v12, v13, v10
	v_fma_f32 v0, -v0, v12, v11
	v_div_fmas_f32 v0, v0, v10, v12
	v_div_fixup_f32 v8, v0, v8, v7
	v_pk_mul_f32 v[2:3], v[8:9], v[2:3]
	s_nop 0
	v_cvt_pk_f16_f32 v7, v2, v3
	v_mov_b32_e32 v248, v6
	v_mov_b32_e32 v249, v7
	s_nop 1
	v_permlane32_swap_b32 v246, v248
	v_permlane32_swap_b32 v247, v249
	global_store_dwordx4 v[232:233], v[246:249], off offset:96
	s_branch .LBB0_630
